# v19: v18 + LDS read-ahead (ring of free registers, counted lgkmcnt) in the MFMA chains of dil/hg1/rt1/hg2/rt2
# baseline (speedup 1.0000x reference)
; #define LAS __attribute__((address_space(3)))
; __device__ __forceinline__ unsigned pk2(float lo, float hi) { return pg8::cvt_pk_bf16(lo, hi); }
; #define MFMA16(a, b, c) __builtin_amdgcn_mfma_f32_16x16x32_bf16((a), (b), (c), 0, 0, 0)
; __device__ __forceinline__ void dil_run(const Ctx& X, bf16* H, int l, int run) {
;     ...
;         for (int t = 0; t < 3; ++t) { f32x4 acc[2] = {(f32x4){0.f, 0.f, 0.f, 0.f}, (f32x4){0.f, 0.f, 0.f, 0.f}}; const int rrow = (64 * nb + 128 + 48 * kq + 16 * t) % 192;
; #pragma unroll
;             for (int ks = 0; ks < 4; ++ks) { const bf16x8 a = ldsfrag(KN, rrow + fr, 272, 32 * ks + 8 * fq); acc[0] = MFMA16(a, qf[0][ks], acc[0]); acc[1] = MFMA16(a, qf[1][ks], acc[1]); }
; #pragma unroll
;             for (int u = 0; u < 2; ++u) { float p[4];
; #pragma unroll
;                 for (int j = 0; j < 4; ++j) acc[u][j] += tb[16 * t + j - 16 * u];
;                 if (edge_lo || edge_hi) {
; #pragma unroll
;                     for (int j = 0; j < 4; ++j) { const int kj = 64 * nb - 64 + 48 * kq + 16 * t + 4 * fq + j; if (kj < 0 || kj >= Ls) acc[u][j] = -1e30f; } }
; #pragma unroll
;                 for (int j = 0; j < 4; ++j) { p[j] = __builtin_amdgcn_exp2f(acc[u][j]); lloc[u] += p[j]; }
;                 v2u w; w.x = pk2(p[0], p[1]); w.y = pk2(p[2], p[3]); *(LAS v2u*)(P + (32 * qh + 16 * u + fr) * 400 + (48 * kq + 16 * t + 4 * fq) * 2) = w; } }
.LBB0_275:
	s_cmp_eq_u32 s75, 0
	s_cselect_b64 s[16:17], -1, 0
	s_cmp_eq_u32 s34, s75
	s_cselect_b64 s[48:49], -1, 0
	s_add_i32 s79, s78, s30
	s_add_i32 s50, s79, 0x80
	s_or_b64 s[16:17], s[16:17], s[48:49]
	s_mul_hi_i32 s48, s50, 0x2aaaaaab
	s_lshr_b32 s49, s48, 31
	s_lshr_b32 s48, s48, 5
	s_add_i32 s48, s48, s49
	s_mulk_i32 s48, 0xc0
	s_sub_i32 s48, s50, s48
	v_or_b32_e32 v90, s48, v113
	s_waitcnt lgkmcnt(0)
	s_barrier
	v_mad_i32_i24 v244, v90, s27, v136
	ds_read_b128 v[164:167], v244
	ds_read_b128 v[180:183], v244 offset:64
	ds_read2_b32 v[184:185], v135 offset0:63 offset1:66
	ds_read_b128 v[188:191], v244 offset:128
	ds_read_b128 v[200:203], v244 offset:192
	ds_read2_b32 v[204:205], v135 offset0:64 offset1:65
	s_waitcnt lgkmcnt(5)
	v_mfma_f32_16x16x32_bf16 v[98:101], v[164:167], v[58:61], 0
	v_add_u32_e32 v96, s30, v172
	v_subrev_u32_e32 v105, 64, v96
	v_mfma_f32_16x16x32_bf16 v[90:93], v[164:167], v[74:77], 0
	v_cmp_lt_i32_e64 s[50:51], -1, v105
	s_andn2_b64 vcc, exec, s[16:17]
	v_cmp_gt_u32_e64 s[58:59], s23, v105
	s_waitcnt lgkmcnt(4)
	v_mfma_f32_16x16x32_bf16 v[98:101], v[180:183], v[62:65], v[98:101]
	v_mfma_f32_16x16x32_bf16 v[90:93], v[180:183], v[78:81], v[90:93]
	s_waitcnt lgkmcnt(2)
	v_mfma_f32_16x16x32_bf16 v[98:101], v[188:191], v[66:69], v[98:101]
	v_mfma_f32_16x16x32_bf16 v[90:93], v[188:191], v[82:85], v[90:93]
	s_waitcnt lgkmcnt(1)
	v_mfma_f32_16x16x32_bf16 v[98:101], v[200:203], v[70:73], v[98:101]
	s_nop 7
	v_add_f32_e32 v97, v98, v184
	v_mfma_f32_16x16x32_bf16 v[90:93], v[200:203], v[86:89], v[90:93]
	v_mov_b32_e32 v98, v99
	v_mov_b32_e32 v99, v100
	s_waitcnt lgkmcnt(0)
	v_pk_add_f32 v[94:95], v[98:99], v[204:205]
	v_add_f32_e32 v100, v101, v185
	v_cndmask_b32_e64 v98, 0, 1, s[16:17]
	v_subrev_u32_e32 v103, 63, v96
	v_subrev_u32_e32 v102, 62, v96
	v_subrev_u32_e32 v101, 61, v96
	v_cmp_ne_u32_e64 s[48:49], 1, v98
	v_cmp_gt_i32_e64 s[56:57], s23, v103
	v_cmp_gt_i32_e64 s[54:55], s23, v102
	v_cmp_gt_i32_e64 s[52:53], s23, v101
	s_waitcnt lgkmcnt(0)
	s_cbranch_vccnz .LBB0_277
	s_and_b64 vcc, s[50:51], s[56:57]
	v_cndmask_b32_e32 v94, v196, v94, vcc
	s_and_b64 vcc, s[50:51], s[54:55]
	v_cndmask_b32_e32 v95, v196, v95, vcc
	s_and_b64 vcc, s[50:51], s[52:53]
	v_cndmask_b32_e64 v97, v196, v97, s[58:59]
	v_cndmask_b32_e32 v100, v196, v100, vcc

; #define LAS __attribute__((address_space(3)))
; __device__ __forceinline__ unsigned pk2(float lo, float hi) { return pg8::cvt_pk_bf16(lo, hi); }
; #define MFMA16(a, b, c) __builtin_amdgcn_mfma_f32_16x16x32_bf16((a), (b), (c), 0, 0, 0)
; __device__ __forceinline__ void dil_run(const Ctx& X, bf16* H, int l, int run) {
;     ...
;         for (int t = 0; t < 3; ++t) { f32x4 acc[2] = {(f32x4){0.f, 0.f, 0.f, 0.f}, (f32x4){0.f, 0.f, 0.f, 0.f}}; const int rrow = (64 * nb + 128 + 48 * kq + 16 * t) % 192;
; #pragma unroll
;             for (int ks = 0; ks < 4; ++ks) { const bf16x8 a = ldsfrag(KN, rrow + fr, 272, 32 * ks + 8 * fq); acc[0] = MFMA16(a, qf[0][ks], acc[0]); acc[1] = MFMA16(a, qf[1][ks], acc[1]); }
; #pragma unroll
;             for (int u = 0; u < 2; ++u) { float p[4];
; #pragma unroll
;                 for (int j = 0; j < 4; ++j) acc[u][j] += tb[16 * t + j - 16 * u];
;                 if (edge_lo || edge_hi) {
; #pragma unroll
;                     for (int j = 0; j < 4; ++j) { const int kj = 64 * nb - 64 + 48 * kq + 16 * t + 4 * fq + j; if (kj < 0 || kj >= Ls) acc[u][j] = -1e30f; } }
; #pragma unroll
;                 for (int j = 0; j < 4; ++j) { p[j] = __builtin_amdgcn_exp2f(acc[u][j]); lloc[u] += p[j]; }
;                 v2u w; w.x = pk2(p[0], p[1]); w.y = pk2(p[2], p[3]); *(LAS v2u*)(P + (32 * qh + 16 * u + fr) * 400 + (48 * kq + 16 * t + 4 * fq) * 2) = w; } }
.LBB0_279:
	s_nop 0
	v_exp_f32_e32 v101, v92
	v_exp_f32_e32 v102, v90
	v_exp_f32_e32 v103, v91
	v_exp_f32_e32 v104, v93
	s_add_i32 s16, s79, 0x90
	s_mul_hi_i32 s17, s16, 0x2aaaaaab
	s_lshr_b32 s50, s17, 31
	s_lshr_b32 s17, s17, 5
	s_add_i32 s17, s17, s50
	v_cvt_pk_bf16_f32 v90, v101, v102
	v_cvt_pk_bf16_f32 v91, v103, v104
	ds_write_b64 v154, v[90:91] offset:6400
	s_mulk_i32 s17, 0xc0
	s_sub_i32 s16, s16, s17
	v_or_b32_e32 v244, s16, v113
	v_mad_i32_i24 v245, v244, s27, v136
	ds_read_b128 v[164:167], v245
	ds_read_b128 v[184:187], v245 offset:64
	ds_read2_b32 v[106:107], v135 offset0:79 offset1:82
	ds_read_b128 v[188:191], v245 offset:128
	ds_read_b128 v[200:203], v245 offset:192
	ds_read2_b32 v[204:205], v135 offset0:80 offset1:81
	s_waitcnt lgkmcnt(5)
	v_mfma_f32_16x16x32_bf16 v[174:177], v[164:167], v[58:61], 0
	v_subrev_u32_e32 v173, 48, v96
	s_movk_i32 s16, 0xffef
	v_mfma_f32_16x16x32_bf16 v[90:93], v[164:167], v[74:77], 0
	v_cmp_lt_i32_e64 s[50:51], s16, v105
	s_and_b64 vcc, exec, s[48:49]
	v_cmp_gt_u32_e64 s[58:59], s23, v173
	s_waitcnt lgkmcnt(4)
	v_mfma_f32_16x16x32_bf16 v[174:177], v[184:187], v[62:65], v[174:177]
	v_mfma_f32_16x16x32_bf16 v[90:93], v[184:187], v[78:81], v[90:93]
	s_waitcnt lgkmcnt(2)
	v_mfma_f32_16x16x32_bf16 v[174:177], v[188:191], v[66:69], v[174:177]
	v_mfma_f32_16x16x32_bf16 v[90:93], v[188:191], v[82:85], v[90:93]
	s_waitcnt lgkmcnt(1)
	v_mfma_f32_16x16x32_bf16 v[174:177], v[200:203], v[70:73], v[174:177]
	s_nop 7
	v_add_f32_e32 v106, v174, v106
	v_mfma_f32_16x16x32_bf16 v[90:93], v[200:203], v[86:89], v[90:93]
	v_mov_b32_e32 v162, v175
	v_mov_b32_e32 v163, v176
	v_subrev_u32_e32 v176, 47, v96
	v_subrev_u32_e32 v175, 46, v96
	v_subrev_u32_e32 v174, 45, v96
	s_waitcnt lgkmcnt(0)
	v_pk_add_f32 v[94:95], v[162:163], v[204:205]
	v_add_f32_e32 v107, v177, v107
	v_cmp_gt_i32_e64 s[56:57], s23, v176
	v_cmp_gt_i32_e64 s[54:55], s23, v175
	v_cmp_gt_i32_e64 s[52:53], s23, v174
	s_waitcnt lgkmcnt(0)
	s_cbranch_vccnz .LBB0_281
	s_and_b64 vcc, s[50:51], s[56:57]
	v_cndmask_b32_e32 v94, v196, v94, vcc
	s_and_b64 vcc, s[50:51], s[54:55]
	v_cndmask_b32_e32 v95, v196, v95, vcc
	s_and_b64 vcc, s[50:51], s[52:53]
	v_cndmask_b32_e64 v106, v196, v106, s[58:59]
	v_cndmask_b32_e32 v107, v196, v107, vcc

; #define LAS __attribute__((address_space(3)))
; __device__ __forceinline__ unsigned pk2(float lo, float hi) { return pg8::cvt_pk_bf16(lo, hi); }
; #define MFMA16(a, b, c) __builtin_amdgcn_mfma_f32_16x16x32_bf16((a), (b), (c), 0, 0, 0)
; __device__ __forceinline__ void dil_run(const Ctx& X, bf16* H, int l, int run) {
;     ...
;         for (int t = 0; t < 3; ++t) { f32x4 acc[2] = {(f32x4){0.f, 0.f, 0.f, 0.f}, (f32x4){0.f, 0.f, 0.f, 0.f}}; const int rrow = (64 * nb + 128 + 48 * kq + 16 * t) % 192;
; #pragma unroll
;             for (int ks = 0; ks < 4; ++ks) { const bf16x8 a = ldsfrag(KN, rrow + fr, 272, 32 * ks + 8 * fq); acc[0] = MFMA16(a, qf[0][ks], acc[0]); acc[1] = MFMA16(a, qf[1][ks], acc[1]); }
; #pragma unroll
;             for (int u = 0; u < 2; ++u) { float p[4];
; #pragma unroll
;                 for (int j = 0; j < 4; ++j) acc[u][j] += tb[16 * t + j - 16 * u];
;                 if (edge_lo || edge_hi) {
; #pragma unroll
;                     for (int j = 0; j < 4; ++j) { const int kj = 64 * nb - 64 + 48 * kq + 16 * t + 4 * fq + j; if (kj < 0 || kj >= Ls) acc[u][j] = -1e30f; } }
; #pragma unroll
;                 for (int j = 0; j < 4; ++j) { p[j] = __builtin_amdgcn_exp2f(acc[u][j]); lloc[u] += p[j]; }
;                 v2u w; w.x = pk2(p[0], p[1]); w.y = pk2(p[2], p[3]); *(LAS v2u*)(P + (32 * qh + 16 * u + fr) * 400 + (48 * kq + 16 * t + 4 * fq) * 2) = w; } }
.LBB0_283:
	s_nop 0
	v_exp_f32_e32 v92, v92
	v_exp_f32_e32 v90, v90
	v_exp_f32_e32 v91, v91
	v_exp_f32_e32 v93, v93
	s_addk_i32 s79, 0xa0
	s_mul_hi_i32 s16, s79, 0x2aaaaaab
	s_lshr_b32 s17, s16, 31
	s_lshr_b32 s16, s16, 5
	s_add_i32 s16, s16, s17
	v_cvt_pk_bf16_f32 v162, v92, v90
	v_cvt_pk_bf16_f32 v163, v91, v93
	ds_write_b64 v154, v[162:163] offset:6432
	s_mulk_i32 s16, 0xc0
	s_sub_i32 s16, s79, s16
	v_or_b32_e32 v244, s16, v113
	v_mad_i32_i24 v245, v244, s27, v136
	ds_read_b128 v[164:167], v245
	ds_read_b128 v[174:177], v245 offset:64
	ds_read_b128 v[180:183], v245 offset:128
	ds_read_b128 v[184:187], v245 offset:192
	s_waitcnt lgkmcnt(3)
	v_mfma_f32_16x16x32_bf16 v[58:61], v[164:167], v[58:61], 0
	s_movk_i32 s16, 0xffdf
	v_cmp_lt_i32_e64 s[50:51], s16, v105
	s_and_b64 vcc, exec, s[48:49]
	v_mfma_f32_16x16x32_bf16 v[74:77], v[164:167], v[74:77], 0
	s_waitcnt lgkmcnt(2)
	v_mfma_f32_16x16x32_bf16 v[58:61], v[174:177], v[62:65], v[58:61]
	v_mfma_f32_16x16x32_bf16 v[62:65], v[174:177], v[78:81], v[74:77]
	s_waitcnt lgkmcnt(1)
	v_mfma_f32_16x16x32_bf16 v[58:61], v[180:183], v[66:69], v[58:61]
	ds_read2_b32 v[66:67], v135 offset0:95 offset1:98
	ds_read2_b32 v[188:189], v135 offset0:96 offset1:97
	v_mfma_f32_16x16x32_bf16 v[62:65], v[180:183], v[82:85], v[62:65]
	s_waitcnt lgkmcnt(2)
	v_mfma_f32_16x16x32_bf16 v[70:73], v[184:187], v[70:73], v[58:61]
	v_mfma_f32_16x16x32_bf16 v[58:61], v[184:187], v[86:89], v[62:65]
	s_nop 6
	v_mov_b32_e32 v68, v71
	v_mov_b32_e32 v69, v72
	v_subrev_u32_e32 v64, 32, v96
	s_waitcnt lgkmcnt(1)
	v_add_f32_e32 v65, v70, v66
	v_subrev_u32_e32 v66, 29, v96
	v_cmp_gt_u32_e64 s[58:59], s23, v64
	s_waitcnt lgkmcnt(0)
	v_pk_add_f32 v[62:63], v[68:69], v[188:189]
	v_add_f32_e32 v69, v73, v67
	v_subrev_u32_e32 v68, 31, v96
	v_subrev_u32_e32 v67, 30, v96
	v_cmp_gt_i32_e64 s[56:57], s23, v68
	v_cmp_gt_i32_e64 s[54:55], s23, v67
	v_cmp_gt_i32_e64 s[52:53], s23, v66
	s_waitcnt lgkmcnt(0)
	s_cbranch_vccnz .LBB0_285
	s_and_b64 vcc, s[50:51], s[56:57]
	v_cndmask_b32_e32 v62, v196, v62, vcc
	s_and_b64 vcc, s[50:51], s[54:55]
	v_cndmask_b32_e32 v63, v196, v63, vcc
	s_and_b64 vcc, s[50:51], s[52:53]
	v_cndmask_b32_e64 v65, v196, v65, s[58:59]
	v_cndmask_b32_e32 v69, v196, v69, vcc

; #define MFMA16(a, b, c) __builtin_amdgcn_mfma_f32_16x16x32_bf16((a), (b), (c), 0, 0, 0)
; __device__ __forceinline__ void dil_run(const Ctx& X, bf16* H, int l, int run) {
;     ...
;         const int dh = kh; const float lrow = (lx[qi] + lx[64 + qi]) + (lx[128 + qi] + lx[192 + qi]); const float inv = __builtin_amdgcn_rcpf(lrow);
;         f32x4 oo[4];
; #pragma unroll
;         for (int t = 0; t < 4; ++t) oo[t] = (f32x4){0.f, 0.f, 0.f, 0.f};
; #pragma unroll
;         for (int ks = 0; ks < 6; ++ks) { const bf16x8 bb = ldsfrag(P, qi, 400, 32 * ks + 8 * fq); const int rcol = (64 * nb + 128 + 32 * ks) % 192;
; #pragma unroll
;             for (int t = 0; t < 4; ++t) { const bf16x8 a = vtfrag(VT, 64 * dh + 16 * t + fr, 400, rcol + 8 * fq); oo[t] = MFMA16(a, bb, oo[t]); } }
.LBB0_291:
	s_or_b64 exec, exec, s[16:17]
	s_waitcnt lgkmcnt(0)
	s_barrier
	s_nop 2
	ds_read2st64_b32 v[84:85], v138 offset1:1
	ds_read2st64_b32 v[60:61], v138 offset0:2 offset1:3
	ds_read_b128 v[88:91], v150
	s_add_i32 s16, s77, s30
	s_add_i32 s17, s16, 0x80
	s_mul_hi_i32 s48, s17, 0x2aaaaaab
	s_lshr_b32 s49, s48, 31
	s_lshr_b32 s48, s48, 5
	s_add_i32 s48, s48, s49
	s_mulk_i32 s48, 0xc0
	s_sub_i32 s17, s17, s48
	v_bitop3_b32 v244, s17, v141, v139 bitop3:0x36
	v_lshl_add_u32 v245, v244, 1, v140
	ds_read_b128 v[92:95], v245 offset:52224
	v_bitop3_b32 v244, s17, v143, v139 bitop3:0x36
	v_lshl_add_u32 v245, v244, 1, v142
	ds_read_b128 v[96:99], v245 offset:52224
	v_bitop3_b32 v244, s17, v145, v139 bitop3:0x36
	v_lshl_add_u32 v245, v244, 1, v144
	ds_read_b128 v[100:103], v245 offset:52224
	v_bitop3_b32 v244, s17, v147, v139 bitop3:0x36
	v_lshl_add_u32 v245, v244, 1, v146
	ds_read_b128 v[104:107], v245 offset:52224
	s_add_i32 s17, s16, 0xa0
	s_waitcnt lgkmcnt(6)
	v_mov_b32_e32 v62, v84
	s_waitcnt lgkmcnt(5)
	v_mov_b32_e32 v63, v60
	v_mov_b32_e32 v60, v85
	v_pk_add_f32 v[58:59], v[62:63], v[60:61]
	v_add_f32_e32 v58, v58, v59
	s_mul_hi_i32 s48, s17, 0x2aaaaaab
	s_lshr_b32 s49, s48, 31
	s_lshr_b32 s48, s48, 5
	s_add_i32 s48, s48, s49
	s_mulk_i32 s48, 0xc0
	s_sub_i32 s17, s17, s48
	v_bitop3_b32 v244, s17, v141, v139 bitop3:0x36
	v_lshl_add_u32 v245, v244, 1, v140
	ds_read_b128 v[164:167], v245 offset:52224
	ds_read_b128 v[180:183], v150 offset:64
	v_bitop3_b32 v244, s17, v143, v139 bitop3:0x36
	v_lshl_add_u32 v245, v244, 1, v142
	ds_read_b128 v[184:187], v245 offset:52224
	v_bitop3_b32 v244, s17, v145, v139 bitop3:0x36
	v_lshl_add_u32 v245, v244, 1, v144
	ds_read_b128 v[188:191], v245 offset:52224
	v_bitop3_b32 v244, s17, v147, v139 bitop3:0x36
	v_lshl_add_u32 v245, v244, 1, v146
	ds_read_b128 v[200:203], v245 offset:52224
	ds_read_b128 v[204:207], v150 offset:128
	s_add_i32 s17, s16, 0xc0
	s_waitcnt lgkmcnt(9)
	v_mfma_f32_16x16x32_bf16 v[64:67], v[92:95], v[88:91], 0
	s_waitcnt lgkmcnt(8)
	v_mfma_f32_16x16x32_bf16 v[68:71], v[96:99], v[88:91], 0
	s_waitcnt lgkmcnt(7)
	v_mfma_f32_16x16x32_bf16 v[72:75], v[100:103], v[88:91], 0
	s_waitcnt lgkmcnt(6)
	v_mfma_f32_16x16x32_bf16 v[60:63], v[104:107], v[88:91], 0
	s_waitcnt lgkmcnt(4)
	v_mfma_f32_16x16x32_bf16 v[64:67], v[164:167], v[180:183], v[64:67]
	s_waitcnt lgkmcnt(3)
	v_mfma_f32_16x16x32_bf16 v[68:71], v[184:187], v[180:183], v[68:71]
	s_waitcnt lgkmcnt(2)
	v_mfma_f32_16x16x32_bf16 v[72:75], v[188:191], v[180:183], v[72:75]
	s_mul_hi_i32 s48, s17, 0x2aaaaaab
	s_lshr_b32 s49, s48, 31
	s_lshr_b32 s48, s48, 5
	s_add_i32 s48, s48, s49
	s_mulk_i32 s48, 0xc0
	s_sub_i32 s17, s17, s48
	v_bitop3_b32 v244, s17, v141, v139 bitop3:0x36
	v_lshl_add_u32 v245, v244, 1, v140
	ds_read_b128 v[208:211], v245 offset:52224
	v_bitop3_b32 v244, s17, v143, v139 bitop3:0x36
	v_lshl_add_u32 v245, v244, 1, v142
	ds_read_b128 v[212:215], v245 offset:52224
	v_bitop3_b32 v244, s17, v145, v139 bitop3:0x36
	v_lshl_add_u32 v245, v244, 1, v144
	ds_read_b128 v[216:219], v245 offset:52224
	v_bitop3_b32 v244, s17, v147, v139 bitop3:0x36
	v_lshl_add_u32 v245, v244, 1, v146
	ds_read_b128 v[220:223], v245 offset:52224
	ds_read_b128 v[224:227], v150 offset:192
	s_add_i32 s17, s16, 0xe0
	s_waitcnt lgkmcnt(6)
	v_mfma_f32_16x16x32_bf16 v[60:63], v[200:203], v[180:183], v[60:63]
	s_waitcnt lgkmcnt(4)
	v_mfma_f32_16x16x32_bf16 v[64:67], v[208:211], v[204:207], v[64:67]
	s_waitcnt lgkmcnt(3)
	v_mfma_f32_16x16x32_bf16 v[68:71], v[212:215], v[204:207], v[68:71]
	s_waitcnt lgkmcnt(2)
	v_mfma_f32_16x16x32_bf16 v[72:75], v[216:219], v[204:207], v[72:75]
	s_mul_hi_i32 s48, s17, 0x2aaaaaab
	s_lshr_b32 s49, s48, 31
	s_lshr_b32 s48, s48, 5
	s_add_i32 s48, s48, s49
	s_mulk_i32 s48, 0xc0
	s_sub_i32 s17, s17, s48
	v_bitop3_b32 v244, s17, v141, v139 bitop3:0x36
	v_lshl_add_u32 v245, v244, 1, v140
	ds_read_b128 v[228:231], v245 offset:52224
	v_bitop3_b32 v244, s17, v143, v139 bitop3:0x36
	v_lshl_add_u32 v245, v244, 1, v142
	ds_read_b128 v[232:235], v245 offset:52224
	v_bitop3_b32 v244, s17, v145, v139 bitop3:0x36
	v_lshl_add_u32 v245, v244, 1, v144
	ds_read_b128 v[236:239], v245 offset:52224
	v_bitop3_b32 v244, s17, v147, v139 bitop3:0x36
	v_lshl_add_u32 v245, v244, 1, v146
	ds_read_b128 v[240:243], v245 offset:52224
	ds_read_b128 v[84:87], v150 offset:256
	s_add_i32 s17, s16, 0x100
	s_waitcnt lgkmcnt(6)
	v_mfma_f32_16x16x32_bf16 v[60:63], v[220:223], v[204:207], v[60:63]
	s_waitcnt lgkmcnt(4)
	v_mfma_f32_16x16x32_bf16 v[64:67], v[228:231], v[224:227], v[64:67]
	s_waitcnt lgkmcnt(3)
	v_mfma_f32_16x16x32_bf16 v[68:71], v[232:235], v[224:227], v[68:71]
	s_waitcnt lgkmcnt(2)
	v_mfma_f32_16x16x32_bf16 v[72:75], v[236:239], v[224:227], v[72:75]
	s_mul_hi_i32 s48, s17, 0x2aaaaaab
	s_lshr_b32 s49, s48, 31
	s_lshr_b32 s48, s48, 5
	s_add_i32 s48, s48, s49
	s_mulk_i32 s48, 0xc0
	s_sub_i32 s17, s17, s48
	v_bitop3_b32 v244, s17, v141, v139 bitop3:0x36
	v_lshl_add_u32 v245, v244, 1, v140
	ds_read_b128 v[92:95], v245 offset:52224
	v_bitop3_b32 v244, s17, v143, v139 bitop3:0x36
	v_lshl_add_u32 v245, v244, 1, v142
	ds_read_b128 v[96:99], v245 offset:52224
	v_bitop3_b32 v244, s17, v145, v139 bitop3:0x36
	v_lshl_add_u32 v245, v244, 1, v144
	ds_read_b128 v[100:103], v245 offset:52224
	v_bitop3_b32 v244, s17, v147, v139 bitop3:0x36
	v_lshl_add_u32 v245, v244, 1, v146
	ds_read_b128 v[88:91], v245 offset:52224
	ds_read_b128 v[76:79], v150 offset:320
	s_addk_i32 s16, 0x120
	s_waitcnt lgkmcnt(6)
	v_mfma_f32_16x16x32_bf16 v[60:63], v[240:243], v[224:227], v[60:63]
	s_waitcnt lgkmcnt(4)
	v_mfma_f32_16x16x32_bf16 v[64:67], v[92:95], v[84:87], v[64:67]
	s_waitcnt lgkmcnt(3)
	v_mfma_f32_16x16x32_bf16 v[68:71], v[96:99], v[84:87], v[68:71]
	s_waitcnt lgkmcnt(2)
	v_mfma_f32_16x16x32_bf16 v[72:75], v[100:103], v[84:87], v[72:75]
	s_mul_hi_i32 s17, s16, 0x2aaaaaab
	s_lshr_b32 s48, s17, 31
	s_lshr_b32 s17, s17, 5
	s_add_i32 s17, s17, s48
	s_mulk_i32 s17, 0xc0
	s_sub_i32 s16, s16, s17
	v_bitop3_b32 v244, s16, v141, v139 bitop3:0x36
	v_lshl_add_u32 v245, v244, 1, v140
	ds_read_b128 v[104:107], v245 offset:52224
	v_bitop3_b32 v244, s16, v143, v139 bitop3:0x36
	v_lshl_add_u32 v245, v244, 1, v142
	ds_read_b128 v[164:167], v245 offset:52224
	v_bitop3_b32 v244, s16, v145, v139 bitop3:0x36
	v_lshl_add_u32 v245, v244, 1, v144
	ds_read_b128 v[184:187], v245 offset:52224
	v_bitop3_b32 v244, s16, v147, v139 bitop3:0x36
	v_lshl_add_u32 v245, v244, 1, v146
	ds_read_b128 v[80:83], v245 offset:52224
	s_waitcnt lgkmcnt(5)
	v_mfma_f32_16x16x32_bf16 v[60:63], v[88:91], v[84:87], v[60:63]
	s_waitcnt lgkmcnt(3)
	v_mfma_f32_16x16x32_bf16 v[64:67], v[104:107], v[76:79], v[64:67]
	s_waitcnt lgkmcnt(2)
	v_mfma_f32_16x16x32_bf16 v[68:71], v[164:167], v[76:79], v[68:71]
	s_waitcnt lgkmcnt(1)
	v_mfma_f32_16x16x32_bf16 v[72:75], v[184:187], v[76:79], v[72:75]
	s_waitcnt lgkmcnt(0)
	s_barrier
; #define LAS __attribute__((address_space(3)))
; #define BAR_LDS() do { asm volatile("s_waitcnt lgkmcnt(0)" ::: "memory"); __builtin_amdgcn_s_barrier(); asm volatile("" ::: "memory"); } while (0)
; __device__ __forceinline__ unsigned pk2(float lo, float hi) { return pg8::cvt_pk_bf16(lo, hi); }
; #define MFMA16(a, b, c) __builtin_amdgcn_mfma_f32_16x16x32_bf16((a), (b), (c), 0, 0, 0)
; __device__ __forceinline__ void dil_run(const Ctx& X, bf16* H, int l, int run) {
;     ...
;             for (int t = 0; t < 4; ++t) { const bf16x8 a = vtfrag(VT, 64 * dh + 16 * t + fr, 400, rcol + 8 * fq); oo[t] = MFMA16(a, bb, oo[t]); } }
;         BAR_LDS();
; #pragma unroll
;         for (int t = 0; t < 4; ++t) { v2u w; w.x = pk2(oo[t][0] * inv, oo[t][1] * inv); w.y = pk2(oo[t][2] * inv, oo[t][3] * inv); *(LAS v2u*)(P + qi * 272 + (64 * dh + 16 * t + 4 * fq) * 2) = w; }
;         if (dh == 0 && fq == 0) ((float*)(X.ws + WS_LSE))[((size_t)g * M + (size_t)b * SEQ + qtok) * 4 + slot] = 0.6931471805599453f * (mshift + __log2f(lrow));
	s_waitcnt lgkmcnt(0)
	v_mfma_f32_16x16x32_bf16 v[60:63], v[80:83], v[76:79], v[60:63]
	v_rcp_f32_e32 v76, v58
	s_nop 0
	v_pk_mul_f32 v[64:65], v[76:77], v[64:65] op_sel_hi:[0,1]
	v_pk_mul_f32 v[66:67], v[76:77], v[66:67] op_sel_hi:[0,1]
	v_cvt_pk_bf16_f32 v64, v64, v65
	v_cvt_pk_bf16_f32 v65, v66, v67
	v_pk_mul_f32 v[66:67], v[76:77], v[68:69] op_sel_hi:[0,1]
	v_pk_mul_f32 v[68:69], v[76:77], v[70:71] op_sel_hi:[0,1]
	v_cvt_pk_bf16_f32 v66, v66, v67
	v_cvt_pk_bf16_f32 v67, v68, v69
	ds_write2_b64 v151, v[64:65], v[66:67] offset1:4
	v_pk_mul_f32 v[64:65], v[76:77], v[72:73] op_sel_hi:[0,1]
	v_pk_mul_f32 v[66:67], v[76:77], v[74:75] op_sel_hi:[0,1]
	v_pk_mul_f32 v[60:61], v[76:77], v[60:61] op_sel_hi:[0,1]
	v_pk_mul_f32 v[62:63], v[76:77], v[62:63] op_sel_hi:[0,1]
	v_cvt_pk_bf16_f32 v64, v64, v65
	v_cvt_pk_bf16_f32 v65, v66, v67
	v_cvt_pk_bf16_f32 v60, v60, v61
	v_cvt_pk_bf16_f32 v61, v62, v63
	ds_write2_b64 v151, v[64:65], v[60:61] offset0:8 offset1:12
	s_and_saveexec_b64 s[16:17], s[66:67]
	s_cbranch_execz .LBB0_293
	v_add_u32_e32 v59, s30, v169
	v_log_f32_e32 v60, v58
	v_lshlrev_b32_e32 v58, s68, v59
	v_add_u32_e32 v58, s70, v58
	v_ashrrev_i32_e32 v59, 31, v58
	v_add_f32_e32 v60, v155, v60
	v_lshl_add_u64 v[58:59], s[12:13], 0, v[58:59]
	v_mul_f32_e32 v60, 0x3f317218, v60
	v_lshl_add_u64 v[58:59], v[58:59], 4, v[124:125]
	global_store_dword v[58:59], v60, off

; #define LAS __attribute__((address_space(3)))
; #define BAR_LDS() do { asm volatile("s_waitcnt lgkmcnt(0)" ::: "memory"); __builtin_amdgcn_s_barrier(); asm volatile("" ::: "memory"); } while (0)
; __device__ __forceinline__ unsigned pk4f8(float a, float b, float c, float d) { int w = __builtin_amdgcn_cvt_pk_fp8_f32(clamp8(a), clamp8(b), 0, false); return (unsigned)__builtin_amdgcn_cvt_pk_fp8_f32(clamp8(c), clamp8(d), w, true); }
; #define MFMA16(a, b, c) __builtin_amdgcn_mfma_f32_16x16x32_bf16((a), (b), (c), 0, 0, 0)
; template <int DK, bool RET, int DIR>
; __device__ __forceinline__ void gla_local_dir(const Ctx& X, int chain, int n, f32x2v lb, unsigned char* St, float* dd) {
;     ...
;         const int fr = X.lane & 15, fq = X.lane >> 4; const int rt = X.wave; constexpr int NCT = 8;
;         f32x4 acc[NCT];
; #pragma unroll
;         for (int t = 0; t < NCT; ++t) acc[t] = (f32x4){0.f, 0.f, 0.f, 0.f};
; #pragma unroll
;         for (int ks = 0; ks < 2; ++ks) { const bf16x8 a = ldsfrag(KC, 16 * rt + fr, 144, 32 * ks + 8 * fq);
; #pragma unroll
;             for (int t = 0; t < NCT; ++t) { const bf16x8 bb = vtfrag(VT, 16 * t + fr, 144, 32 * ks + 8 * fq); acc[t] = MFMA16(a, bb, acc[t]); } }
;         unsigned char* Sp = St + ((size_t)chain * NCH + n) * 128 * DK;
;         const lptr UT = X.lds + L1_END;
; #pragma unroll
;         for (int t = 0; t < NCT; ++t) *(LAS unsigned*)(UT + (16 * t + fr) * 144 + 16 * rt + 4 * fq) = pk4f8(acc[t][0], acc[t][1], acc[t][2], acc[t][3]);
;         BAR_LDS();
; #pragma unroll
;         for (int p = 0; p < 2; ++p) { const int idx = X.tid + NTHR * p, row = idx >> 3, c16 = idx & 7; *(v4u*)(Sp + (size_t)row * DK + 16 * c16) = *(const LAS v4u*)(UT + row * 144 + c16 * 16); }
.LBB0_297:
	s_waitcnt lgkmcnt(0)
	s_barrier
	ds_read_b128 v[84:87], v102 offset:18432
	ds_read_b128 v[116:119], v103
	ds_read_b128 v[120:123], v104 offset:2304
	ds_read_b128 v[132:135], v104 offset:11520
	ds_read_b128 v[136:139], v105 offset:4608
	ds_read_b128 v[140:143], v105 offset:13824
	ds_read_b128 v[144:147], v57 offset:6912
	ds_read_b128 v[148:151], v103 offset:9216
	ds_read_b128 v[152:155], v114
	ds_read_b128 v[76:79], v106 offset:18432
	ds_read_b128 v[164:167], v107
	ds_read_b128 v[168:171], v108 offset:2304
	s_waitcnt lgkmcnt(10)
	v_mfma_f32_16x16x32_bf16 v[30:33], v[84:87], v[116:119], 0
	ds_read_b128 v[180:183], v109 offset:4608
	v_mov_b32_e32 v57, v159
	s_lshl_b64 s[0:1], s[0:1], 21
	s_add_u32 s16, s21, s0
	s_waitcnt lgkmcnt(10)
	v_mfma_f32_16x16x32_bf16 v[34:37], v[84:87], v[120:123], 0
	ds_read_b128 v[184:187], v115 offset:6912
	s_addc_u32 s17, s22, s1
	s_lshl_b64 s[0:1], s[14:15], 14
	s_add_u32 s0, s16, s0
	s_waitcnt lgkmcnt(9)
	v_mfma_f32_16x16x32_bf16 v[38:41], v[84:87], v[136:139], 0
	ds_read_b128 v[188:191], v107 offset:9216
	s_addc_u32 s1, s17, s1
	s_add_i32 s23, s23, s24
	s_and_b64 vcc, exec, s[12:13]
	s_waitcnt lgkmcnt(8)
	v_mfma_f32_16x16x32_bf16 v[60:63], v[84:87], v[144:147], 0
	ds_read_b128 v[200:203], v108 offset:11520
	s_waitcnt lgkmcnt(8)
	v_mfma_f32_16x16x32_bf16 v[64:67], v[84:87], v[148:151], 0
	ds_read_b128 v[204:207], v109 offset:13824
	v_mfma_f32_16x16x32_bf16 v[68:71], v[84:87], v[132:135], 0
	ds_read_b128 v[80:83], v59
	v_mfma_f32_16x16x32_bf16 v[72:75], v[84:87], v[140:143], 0
	s_waitcnt lgkmcnt(9)
	v_mfma_f32_16x16x32_bf16 v[26:29], v[84:87], v[152:155], 0
	s_waitcnt lgkmcnt(7)
	v_mfma_f32_16x16x32_bf16 v[30:33], v[76:79], v[164:167], v[30:33]
	s_waitcnt lgkmcnt(6)
	v_mfma_f32_16x16x32_bf16 v[34:37], v[76:79], v[168:171], v[34:37]
	s_nop 5
	v_med3_f32 v30, v30, s72, v197
	v_med3_f32 v31, v31, s72, v197
	s_waitcnt lgkmcnt(5)
	v_mfma_f32_16x16x32_bf16 v[38:41], v[76:79], v[180:183], v[38:41]
	v_cvt_pk_fp8_f32 v57, v30, v31
	v_med3_f32 v30, v32, s72, v197
	s_waitcnt lgkmcnt(4)
	v_mfma_f32_16x16x32_bf16 v[60:63], v[76:79], v[184:187], v[60:63]
	v_med3_f32 v31, v33, s72, v197
	v_cvt_pk_fp8_f32 v57, v30, v31 op_sel:[0,0,1]
	s_waitcnt lgkmcnt(3)
	v_mfma_f32_16x16x32_bf16 v[64:67], v[76:79], v[188:191], v[64:67]
	v_med3_f32 v30, v34, s72, v197
	v_med3_f32 v31, v35, s72, v197
	v_mov_b32_e32 v32, v159
	v_cvt_pk_fp8_f32 v32, v30, v31
	s_waitcnt lgkmcnt(2)
	v_mfma_f32_16x16x32_bf16 v[68:71], v[76:79], v[200:203], v[68:71]
	v_med3_f32 v30, v36, s72, v197
	v_med3_f32 v31, v37, s72, v197
	v_cvt_pk_fp8_f32 v32, v30, v31 op_sel:[0,0,1]
	s_waitcnt lgkmcnt(1)
	v_mfma_f32_16x16x32_bf16 v[72:75], v[76:79], v[204:207], v[72:75]
	ds_write2st64_b32 v110, v57, v32 offset1:9
	v_med3_f32 v30, v38, s72, v197
	v_med3_f32 v31, v39, s72, v197
	v_mov_b32_e32 v32, v159
	v_cvt_pk_fp8_f32 v32, v30, v31
	v_med3_f32 v30, v40, s72, v197
	v_med3_f32 v31, v41, s72, v197
	v_mov_b32_e32 v33, v159
	v_cvt_pk_fp8_f32 v32, v30, v31 op_sel:[0,0,1]
	v_med3_f32 v30, v60, s72, v197
	v_med3_f32 v31, v61, s72, v197
	v_cvt_pk_fp8_f32 v33, v30, v31
	v_med3_f32 v30, v62, s72, v197
	v_med3_f32 v31, v63, s72, v197
	s_waitcnt lgkmcnt(1)
	v_mfma_f32_16x16x32_bf16 v[26:29], v[76:79], v[80:83], v[26:29]
	v_cvt_pk_fp8_f32 v33, v30, v31 op_sel:[0,0,1]
	v_med3_f32 v30, v64, s72, v197
	v_med3_f32 v31, v65, s72, v197
	ds_write2st64_b32 v110, v32, v33 offset0:18 offset1:27
	v_mov_b32_e32 v32, v159
	v_cvt_pk_fp8_f32 v32, v30, v31
	v_med3_f32 v30, v66, s72, v197
	v_med3_f32 v31, v67, s72, v197
	v_mov_b32_e32 v33, v159
	v_cvt_pk_fp8_f32 v32, v30, v31 op_sel:[0,0,1]
	v_med3_f32 v30, v68, s72, v197
	v_med3_f32 v31, v69, s72, v197
	v_cvt_pk_fp8_f32 v33, v30, v31
	v_med3_f32 v30, v70, s72, v197
	v_med3_f32 v31, v71, s72, v197
	v_med3_f32 v26, v26, s72, v197
	v_cvt_pk_fp8_f32 v33, v30, v31 op_sel:[0,0,1]
	v_med3_f32 v30, v72, s72, v197
	v_med3_f32 v31, v73, s72, v197
	v_med3_f32 v27, v27, s72, v197
	ds_write2st64_b32 v110, v32, v33 offset0:36 offset1:45
	v_mov_b32_e32 v32, v159
	v_cvt_pk_fp8_f32 v32, v30, v31
	v_med3_f32 v30, v74, s72, v197
	v_med3_f32 v31, v75, s72, v197
	v_cvt_pk_fp8_f32 v32, v30, v31 op_sel:[0,0,1]
	v_mov_b32_e32 v30, v159
	v_cvt_pk_fp8_f32 v30, v26, v27
	v_med3_f32 v26, v28, s72, v197
	v_med3_f32 v27, v29, s72, v197
	ds_write_b32 v110, v32 offset:13824
	v_cvt_pk_fp8_f32 v30, v26, v27 op_sel:[0,0,1]
	ds_write_b32 v113, v30
	s_waitcnt lgkmcnt(0)
	s_barrier
	ds_read_b128 v[26:29], v111
	v_lshl_add_u64 v[30:31], s[0:1], 0, v[52:53]
	v_lshl_add_u64 v[30:31], v[30:31], 0, v[50:51]
	s_waitcnt lgkmcnt(0)
	global_store_dwordx4 v[30:31], v[26:29], off
	ds_read_b128 v[26:29], v112
	v_lshl_add_u64 v[30:31], s[0:1], 0, v[54:55]
	v_lshl_add_u64 v[30:31], v[30:31], 0, v[50:51]
	s_mov_b32 s0, s25
	s_waitcnt lgkmcnt(0)
	global_store_dwordx4 v[30:31], v[26:29], off
	s_waitcnt lgkmcnt(0)
	s_barrier
	s_cbranch_vccnz .LBB0_308

; #define LAS __attribute__((address_space(3)))
; #define BAR_LDS() do { asm volatile("s_waitcnt lgkmcnt(0)" ::: "memory"); __builtin_amdgcn_s_barrier(); asm volatile("" ::: "memory"); } while (0)
; __device__ __forceinline__ unsigned pk4f8(float a, float b, float c, float d) { int w = __builtin_amdgcn_cvt_pk_fp8_f32(clamp8(a), clamp8(b), 0, false); return (unsigned)__builtin_amdgcn_cvt_pk_fp8_f32(clamp8(c), clamp8(d), w, true); }
; #define MFMA16(a, b, c) __builtin_amdgcn_mfma_f32_16x16x32_bf16((a), (b), (c), 0, 0, 0)
; template <int DK, bool RET, int DIR>
; __device__ __forceinline__ void gla_local_dir(const Ctx& X, int chain, int n, f32x2v lb, unsigned char* St, float* dd) {
;     ...
;         const int fr = X.lane & 15, fq = X.lane >> 4; const int rt = X.wave; constexpr int NCT = 8;
;         f32x4 acc[NCT];
; #pragma unroll
;         for (int t = 0; t < NCT; ++t) acc[t] = (f32x4){0.f, 0.f, 0.f, 0.f};
; #pragma unroll
;         for (int ks = 0; ks < 2; ++ks) { const bf16x8 a = ldsfrag(KC, 16 * rt + fr, 144, 32 * ks + 8 * fq);
; #pragma unroll
;             for (int t = 0; t < NCT; ++t) { const bf16x8 bb = vtfrag(VT, 16 * t + fr, 144, 32 * ks + 8 * fq); acc[t] = MFMA16(a, bb, acc[t]); } }
;         unsigned char* Sp = St + ((size_t)chain * NCH + n) * 128 * DK;
;         const lptr UT = X.lds + L1_END;
; #pragma unroll
;         for (int t = 0; t < NCT; ++t) *(LAS unsigned*)(UT + (16 * t + fr) * 144 + 16 * rt + 4 * fq) = pk4f8(acc[t][0], acc[t][1], acc[t][2], acc[t][3]);
;         BAR_LDS();
; #pragma unroll
;         for (int p = 0; p < 2; ++p) { const int idx = X.tid + NTHR * p, row = idx >> 3, c16 = idx & 7; *(v4u*)(Sp + (size_t)row * DK + 16 * c16) = *(const LAS v4u*)(UT + row * 144 + c16 * 16); }
;     }
;     BAR_LDS();
.LBB0_304:
	s_waitcnt lgkmcnt(0)
	s_barrier
	s_nop 1
	ds_read_b128 v[116:119], v102 offset:18432
	ds_read_b128 v[120:123], v103
	ds_read_b128 v[132:135], v104 offset:2304
	ds_read_b128 v[136:139], v104 offset:11520
	ds_read_b128 v[140:143], v105 offset:4608
	ds_read_b128 v[144:147], v105 offset:13824
	v_add_u32_e32 v57, v94, v95
	ds_read_b128 v[148:151], v57 offset:6912
	ds_read_b128 v[152:155], v103 offset:9216
	v_add_u32_e32 v114, v97, v95
	ds_read_b128 v[164:167], v114
	ds_read_b128 v[78:81], v106 offset:18432
	ds_read_b128 v[168:171], v107
	ds_read_b128 v[180:183], v108 offset:2304
	s_waitcnt lgkmcnt(10)
	v_mfma_f32_16x16x32_bf16 v[30:33], v[116:119], v[120:123], 0
	ds_read_b128 v[184:187], v109 offset:4608
	v_add_u32_e32 v113, v99, v96
	s_waitcnt lgkmcnt(10)
	v_mfma_f32_16x16x32_bf16 v[34:37], v[116:119], v[132:135], 0
	v_add_u32_e32 v115, v94, v98
	ds_read_b128 v[188:191], v115 offset:6912
	s_lshl_b64 s[16:17], s[0:1], 21
	s_add_u32 s1, s21, s16
	s_addc_u32 s28, s22, s17
	s_waitcnt lgkmcnt(9)
	v_mfma_f32_16x16x32_bf16 v[38:41], v[116:119], v[140:143], 0
	ds_read_b128 v[200:203], v107 offset:9216
	s_lshl_b64 s[16:17], s[14:15], 14
	s_add_u32 s16, s1, s16
	s_addc_u32 s17, s28, s17
	s_waitcnt lgkmcnt(8)
	v_mfma_f32_16x16x32_bf16 v[62:65], v[116:119], v[148:151], 0
	ds_read_b128 v[204:207], v108 offset:11520
	s_or_b32 s0, s0, 1
	s_waitcnt lgkmcnt(8)
	v_mfma_f32_16x16x32_bf16 v[66:69], v[116:119], v[152:155], 0
	ds_read_b128 v[208:211], v109 offset:13824
	v_mfma_f32_16x16x32_bf16 v[70:73], v[116:119], v[136:139], 0
	v_add_u32_e32 v59, v97, v98
	ds_read_b128 v[212:215], v59
	v_mfma_f32_16x16x32_bf16 v[74:77], v[116:119], v[144:147], 0
	s_waitcnt lgkmcnt(9)
	v_mfma_f32_16x16x32_bf16 v[26:29], v[116:119], v[164:167], 0
	s_waitcnt lgkmcnt(7)
	v_mfma_f32_16x16x32_bf16 v[30:33], v[78:81], v[168:171], v[30:33]
	s_waitcnt lgkmcnt(6)
	v_mfma_f32_16x16x32_bf16 v[34:37], v[78:81], v[180:183], v[34:37]
	s_nop 5
	v_med3_f32 v30, v30, s72, v197
	v_med3_f32 v31, v31, s72, v197
	s_waitcnt lgkmcnt(5)
	v_mfma_f32_16x16x32_bf16 v[38:41], v[78:81], v[184:187], v[38:41]
	s_waitcnt lgkmcnt(4)
	v_mfma_f32_16x16x32_bf16 v[62:65], v[78:81], v[188:191], v[62:65]
	s_waitcnt lgkmcnt(3)
	v_mfma_f32_16x16x32_bf16 v[66:69], v[78:81], v[200:203], v[66:69]
	s_waitcnt lgkmcnt(2)
	v_mfma_f32_16x16x32_bf16 v[70:73], v[78:81], v[204:207], v[70:73]
	s_waitcnt lgkmcnt(1)
	v_mfma_f32_16x16x32_bf16 v[74:77], v[78:81], v[208:211], v[74:77]
	s_waitcnt lgkmcnt(0)
	v_mfma_f32_16x16x32_bf16 v[26:29], v[78:81], v[212:215], v[26:29]
	v_mov_b32_e32 v78, v159
	v_cvt_pk_fp8_f32 v78, v30, v31
	v_med3_f32 v30, v32, s72, v197
	v_med3_f32 v31, v33, s72, v197
	v_mov_b32_e32 v32, v159
	v_cvt_pk_fp8_f32 v78, v30, v31 op_sel:[0,0,1]
	v_med3_f32 v30, v34, s72, v197
	v_med3_f32 v31, v35, s72, v197
	v_cvt_pk_fp8_f32 v32, v30, v31
	v_med3_f32 v30, v36, s72, v197
	v_med3_f32 v31, v37, s72, v197
	v_mov_b32_e32 v33, v159
	v_cvt_pk_fp8_f32 v32, v30, v31 op_sel:[0,0,1]
	v_med3_f32 v30, v38, s72, v197
	v_med3_f32 v31, v39, s72, v197
	v_med3_f32 v26, v26, s72, v197
	ds_write2st64_b32 v110, v78, v32 offset1:9
	v_mov_b32_e32 v32, v159
	v_cvt_pk_fp8_f32 v32, v30, v31
	v_med3_f32 v30, v40, s72, v197
	v_med3_f32 v31, v41, s72, v197
	v_med3_f32 v27, v27, s72, v197
	v_cvt_pk_fp8_f32 v32, v30, v31 op_sel:[0,0,1]
	v_med3_f32 v30, v62, s72, v197
	v_med3_f32 v31, v63, s72, v197
	v_cvt_pk_fp8_f32 v33, v30, v31
	v_med3_f32 v30, v64, s72, v197
	v_med3_f32 v31, v65, s72, v197
	v_cvt_pk_fp8_f32 v33, v30, v31 op_sel:[0,0,1]
	v_med3_f32 v30, v66, s72, v197
	v_med3_f32 v31, v67, s72, v197
	ds_write2st64_b32 v110, v32, v33 offset0:18 offset1:27
	v_mov_b32_e32 v32, v159
	v_cvt_pk_fp8_f32 v32, v30, v31
	v_med3_f32 v30, v68, s72, v197
	v_med3_f32 v31, v69, s72, v197
	v_mov_b32_e32 v33, v159
	v_cvt_pk_fp8_f32 v32, v30, v31 op_sel:[0,0,1]
	v_med3_f32 v30, v70, s72, v197
	v_med3_f32 v31, v71, s72, v197
	v_cvt_pk_fp8_f32 v33, v30, v31
	v_med3_f32 v30, v72, s72, v197
	v_med3_f32 v31, v73, s72, v197
	v_cvt_pk_fp8_f32 v33, v30, v31 op_sel:[0,0,1]
	v_med3_f32 v30, v74, s72, v197
	v_med3_f32 v31, v75, s72, v197
	ds_write2st64_b32 v110, v32, v33 offset0:36 offset1:45
	v_mov_b32_e32 v32, v159
	v_cvt_pk_fp8_f32 v32, v30, v31
	v_med3_f32 v30, v76, s72, v197
	v_med3_f32 v31, v77, s72, v197
	v_cvt_pk_fp8_f32 v32, v30, v31 op_sel:[0,0,1]
	v_mov_b32_e32 v30, v159
	v_cvt_pk_fp8_f32 v30, v26, v27
	v_med3_f32 v26, v28, s72, v197
	v_med3_f32 v27, v29, s72, v197
	ds_write_b32 v110, v32 offset:13824
	v_cvt_pk_fp8_f32 v30, v26, v27 op_sel:[0,0,1]
	ds_write_b32 v113, v30
	s_waitcnt lgkmcnt(0)
	s_barrier
	ds_read_b128 v[26:29], v111
	v_lshl_add_u64 v[30:31], s[16:17], 0, v[52:53]
	v_lshl_add_u64 v[30:31], v[30:31], 0, v[50:51]
	s_waitcnt lgkmcnt(0)
	global_store_dwordx4 v[30:31], v[26:29], off
	ds_read_b128 v[26:29], v112
	v_lshl_add_u64 v[30:31], s[16:17], 0, v[54:55]
	v_lshl_add_u64 v[30:31], v[30:31], 0, v[50:51]
	s_waitcnt lgkmcnt(0)
	global_store_dwordx4 v[30:31], v[26:29], off
	s_nop 1
	v_mov_b32_e32 v26, v90
	s_waitcnt lgkmcnt(0)
	s_barrier
; #define LAS __attribute__((address_space(3)))
; __device__ __forceinline__ f32x2v bfpair(unsigned w) { f32x2v r; r.x = __uint_as_float(w << 16); r.y = __uint_as_float(w & 0xffff0000u); return r; }
; __device__ __forceinline__ f32x2v rcp2(f32x2v v) { f32x2v r; r.x = __builtin_amdgcn_rcpf(v.x); r.y = __builtin_amdgcn_rcpf(v.y); return r; }
; template <int DIR, bool NEEDQ>
; __device__ __forceinline__ void gla_prep(lptr rawz, lptr rawq, f32x2v lb, LAS float* seg, int kp, int rg, f32x2v (&c)[8], f32x2v (&qv)[8], f32x2v (&kv)[8]) {
;     f32x2v run = (f32x2v){1.f, 1.f}; const f32x2v oml = 1.0f - lb;
; #pragma unroll
;     for (int i = 0; i < 8; ++i) { const int ii = DIR ? 7 - i : i; const int r = 8 * rg + ii;
;         const f32x2v z = bfpair(*(const LAS unsigned*)(rawz + (r * 128 + 2 * kp) * 2)); f32x2v e; e.x = __expf(-z.x); e.y = __expf(-z.y);
;         const f32x2v f = lb + oml * rcp2(e + 1.0f); run = run * f; kv[ii] = 1.0f - f; c[ii] = run;
;         if (NEEDQ) qv[ii] = bfpair(*(const LAS unsigned*)(rawq + (r * 128 + 2 * kp) * 2)); }
;     *(LAS f32x2v*)(seg + rg * 128 + 2 * kp) = run;
; }
	s_nop 0
	v_readfirstlane_b32 s1, v26
	s_ashr_i32 s15, s1, 6
	s_lshl_b32 s16, s15, 11
	v_and_b32_e32 v116, 63, v26
	s_add_i32 s16, s16, 0
	v_lshl_add_u32 v32, v116, 2, s16
	ds_read2st64_b32 v[28:29], v32 offset0:230 offset1:231
	v_pk_add_f32 v[26:27], v[60:61], 1.0 op_sel_hi:[1,0] neg_lo:[1,0] neg_hi:[1,0]
	s_lshl_b32 s16, s15, 9
	s_add_i32 s16, s16, 0
	s_cmp_gt_i32 s15, 6
	s_waitcnt lgkmcnt(0)
	v_lshlrev_b32_e32 v30, 16, v29
	v_and_b32_e32 v29, 0xffff0000, v29
	v_mul_f32_e32 v30, 0xbfb8aa3b, v30
	v_mul_f32_e32 v29, 0xbfb8aa3b, v29
	v_exp_f32_e32 v30, v30
	v_exp_f32_e32 v31, v29
	v_lshlrev_b32_e32 v29, 16, v28
	s_cselect_b64 vcc, -1, 0
	s_cmp_gt_i32 s15, 5
	v_pk_add_f32 v[30:31], v[30:31], 1.0 op_sel_hi:[1,0]
	s_nop 0
	v_rcp_f32_e32 v30, v30
	v_rcp_f32_e32 v31, v31
	s_nop 0
	v_pk_fma_f32 v[62:63], v[26:27], v[30:31], v[60:61]
	v_and_b32_e32 v30, 0xffff0000, v28
	v_mul_f32_e32 v28, 0xbfb8aa3b, v29
	v_mul_f32_e32 v29, 0xbfb8aa3b, v30
	v_exp_f32_e32 v28, v28
	v_exp_f32_e32 v29, v29
	v_pk_add_f32 v[64:65], v[62:63], 1.0 op_sel_hi:[1,0] neg_lo:[1,0] neg_hi:[1,0]
	v_pk_add_f32 v[28:29], v[28:29], 1.0 op_sel_hi:[1,0]
	s_nop 0
	v_rcp_f32_e32 v28, v28
	v_rcp_f32_e32 v29, v29
	s_nop 0
	v_pk_fma_f32 v[28:29], v[26:27], v[28:29], v[60:61]
	s_nop 0
	v_pk_mul_f32 v[66:67], v[62:63], v[28:29]
	v_pk_add_f32 v[68:69], v[28:29], 1.0 op_sel_hi:[1,0] neg_lo:[1,0] neg_hi:[1,0]
	ds_read2st64_b32 v[28:29], v32 offset0:228 offset1:229
	s_waitcnt lgkmcnt(0)
	v_lshlrev_b32_e32 v30, 16, v29
	v_and_b32_e32 v29, 0xffff0000, v29
	v_mul_f32_e32 v30, 0xbfb8aa3b, v30
	v_mul_f32_e32 v29, 0xbfb8aa3b, v29
	v_exp_f32_e32 v30, v30
	v_exp_f32_e32 v31, v29
	v_lshlrev_b32_e32 v29, 16, v28
	v_pk_add_f32 v[30:31], v[30:31], 1.0 op_sel_hi:[1,0]
	s_nop 0
	v_rcp_f32_e32 v30, v30
	v_rcp_f32_e32 v31, v31
	s_nop 0
	v_pk_fma_f32 v[30:31], v[26:27], v[30:31], v[60:61]
	s_nop 0
	v_pk_mul_f32 v[70:71], v[66:67], v[30:31]
	v_pk_add_f32 v[72:73], v[30:31], 1.0 op_sel_hi:[1,0] neg_lo:[1,0] neg_hi:[1,0]
	v_and_b32_e32 v30, 0xffff0000, v28
	v_mul_f32_e32 v28, 0xbfb8aa3b, v29
	v_mul_f32_e32 v29, 0xbfb8aa3b, v30
	v_exp_f32_e32 v28, v28
	v_exp_f32_e32 v29, v29
	s_nop 0
	v_pk_add_f32 v[28:29], v[28:29], 1.0 op_sel_hi:[1,0]
	s_nop 0
	v_rcp_f32_e32 v28, v28
	v_rcp_f32_e32 v29, v29
	s_nop 0
	v_pk_fma_f32 v[28:29], v[26:27], v[28:29], v[60:61]
	s_nop 0
	v_pk_mul_f32 v[74:75], v[70:71], v[28:29]
	v_pk_add_f32 v[76:77], v[28:29], 1.0 op_sel_hi:[1,0] neg_lo:[1,0] neg_hi:[1,0]
	ds_read2st64_b32 v[28:29], v32 offset0:226 offset1:227
	s_waitcnt lgkmcnt(0)
	v_lshlrev_b32_e32 v30, 16, v29
	v_and_b32_e32 v29, 0xffff0000, v29
	v_mul_f32_e32 v30, 0xbfb8aa3b, v30
	v_mul_f32_e32 v29, 0xbfb8aa3b, v29
	v_exp_f32_e32 v30, v30
	v_exp_f32_e32 v31, v29
	v_lshlrev_b32_e32 v29, 16, v28
	v_pk_add_f32 v[30:31], v[30:31], 1.0 op_sel_hi:[1,0]
	s_nop 0
	v_rcp_f32_e32 v30, v30
	v_rcp_f32_e32 v31, v31
	s_nop 0
	v_pk_fma_f32 v[30:31], v[26:27], v[30:31], v[60:61]
	s_nop 0
	v_pk_mul_f32 v[78:79], v[74:75], v[30:31]
	v_pk_add_f32 v[80:81], v[30:31], 1.0 op_sel_hi:[1,0] neg_lo:[1,0] neg_hi:[1,0]
	v_and_b32_e32 v30, 0xffff0000, v28
	v_mul_f32_e32 v28, 0xbfb8aa3b, v29
	v_mul_f32_e32 v29, 0xbfb8aa3b, v30
	v_exp_f32_e32 v28, v28
	v_exp_f32_e32 v29, v29
	s_nop 0
	v_pk_add_f32 v[28:29], v[28:29], 1.0 op_sel_hi:[1,0]
	s_nop 0
	v_rcp_f32_e32 v28, v28
	v_rcp_f32_e32 v29, v29
	s_nop 0
	v_pk_fma_f32 v[28:29], v[26:27], v[28:29], v[60:61]
	s_nop 0
	v_pk_mul_f32 v[82:83], v[78:79], v[28:29]
	v_pk_add_f32 v[84:85], v[28:29], 1.0 op_sel_hi:[1,0] neg_lo:[1,0] neg_hi:[1,0]
	ds_read2st64_b32 v[28:29], v32 offset0:224 offset1:225
	s_waitcnt lgkmcnt(0)
	v_lshlrev_b32_e32 v30, 16, v29
	v_and_b32_e32 v29, 0xffff0000, v29
	v_mul_f32_e32 v30, 0xbfb8aa3b, v30
	v_mul_f32_e32 v29, 0xbfb8aa3b, v29
	v_exp_f32_e32 v30, v30
	v_exp_f32_e32 v31, v29
	v_lshlrev_b32_e32 v29, 16, v28
	v_pk_add_f32 v[30:31], v[30:31], 1.0 op_sel_hi:[1,0]
	s_nop 0
	v_rcp_f32_e32 v30, v30
	v_rcp_f32_e32 v31, v31
	s_nop 0
	v_pk_fma_f32 v[30:31], v[26:27], v[30:31], v[60:61]
	s_nop 0
	v_pk_mul_f32 v[86:87], v[82:83], v[30:31]
	v_pk_add_f32 v[88:89], v[30:31], 1.0 op_sel_hi:[1,0] neg_lo:[1,0] neg_hi:[1,0]
	v_and_b32_e32 v30, 0xffff0000, v28
	v_mul_f32_e32 v28, 0xbfb8aa3b, v29
	v_mul_f32_e32 v29, 0xbfb8aa3b, v30
	v_exp_f32_e32 v28, v28
	v_exp_f32_e32 v29, v29
	s_nop 0
	v_pk_add_f32 v[28:29], v[28:29], 1.0 op_sel_hi:[1,0]
	s_nop 0
	v_rcp_f32_e32 v28, v28
	v_rcp_f32_e32 v29, v29
	s_nop 0
	v_pk_fma_f32 v[26:27], v[26:27], v[28:29], v[60:61]
	v_lshlrev_b32_e32 v60, 3, v116
	v_pk_mul_f32 v[118:119], v[86:87], v[26:27]
	v_pk_add_f32 v[120:121], v[26:27], 1.0 op_sel_hi:[1,0] neg_lo:[1,0] neg_hi:[1,0]
	v_add_u32_e32 v26, s16, v60
	ds_write_b64 v26, v[118:119] offset:36864
	s_waitcnt lgkmcnt(0)
	s_barrier
; #define LAS __attribute__((address_space(3)))
; __device__ __forceinline__ unsigned pk2(float lo, float hi) { return pg8::cvt_pk_bf16(lo, hi); }
; __device__ __forceinline__ f32x2v rcp2(f32x2v v) { f32x2v r; r.x = __builtin_amdgcn_rcpf(v.x); r.y = __builtin_amdgcn_rcpf(v.y); return r; }
; template <int DK, bool RET, int DIR>
; __device__ __forceinline__ void gla_local_dir(const Ctx& X, int chain, int n, f32x2v lb, unsigned char* St, float* dd) {
;     ...
;         const int sg = DIR ? 7 - rg : rg;
;         f32x2v base = (f32x2v){1.f, 1.f}, all = (f32x2v){1.f, 1.f};
; #pragma unroll
;         for (int j = 0; j < 8; ++j) { const f32x2v T = SEGT(j); all = all * T; if (j >= sg) base = base * T; }
;         f32x2v e[8];
; #pragma unroll
;         for (int ii = 0; ii < 8; ++ii) { f32x2v cc = c[ii]; cc.x = fmaxf(cc.x, 1e-37f); cc.y = fmaxf(cc.y, 1e-37f); e[ii] = kv[ii] * base * rcp2(cc); }
;         v4u w0, w1;
;         w0.x = pk2(e[0].x, e[1].x); w0.y = pk2(e[2].x, e[3].x); w0.z = pk2(e[4].x, e[5].x); w0.w = pk2(e[6].x, e[7].x);
;         w1.x = pk2(e[0].y, e[1].y); w1.y = pk2(e[2].y, e[3].y); w1.z = pk2(e[4].y, e[5].y); w1.w = pk2(e[6].y, e[7].y);
;         *(LAS v4u*)(KC + (2 * kp) * 144 + rg * 16) = w0; *(LAS v4u*)(KC + (2 * kp + 1) * 144 + rg * 16) = w1;
;         if (rg == 0) *(f32x2v*)(dd + ((size_t)chain * NCH + n) * DK + 2 * kp) = all;
	v_add_u32_e32 v61, 0, v60
	ds_read2st64_b64 v[26:29], v61 offset0:78 offset1:79
	v_max_f32_e32 v117, 0x2081cea, v118
	v_max_f32_e32 v124, 0x2081cea, v119
	s_mov_b64 s[16:17], -1
	s_waitcnt lgkmcnt(0)
	v_cndmask_b32_e32 v31, 1.0, v29, vcc
	v_cndmask_b32_e32 v30, 1.0, v28, vcc
	v_pk_mul_f32 v[30:31], v[30:31], v[26:27]
	s_cselect_b64 vcc, -1, 0
	v_cndmask_b32_e32 v35, 1.0, v31, vcc
	v_cndmask_b32_e32 v34, 1.0, v30, vcc
	ds_read2st64_b64 v[30:33], v61 offset0:76 offset1:77
	s_cmp_gt_i32 s15, 4
	s_cselect_b64 vcc, -1, 0
	s_cmp_gt_i32 s15, 3
	s_waitcnt lgkmcnt(0)
	v_pk_mul_f32 v[34:35], v[32:33], v[34:35]
	s_nop 0
	v_cndmask_b32_e32 v35, 1.0, v35, vcc
	v_cndmask_b32_e32 v34, 1.0, v34, vcc
	v_pk_mul_f32 v[34:35], v[30:31], v[34:35]
	s_cselect_b64 vcc, -1, 0
	v_cndmask_b32_e32 v39, 1.0, v35, vcc
	v_cndmask_b32_e32 v38, 1.0, v34, vcc
	ds_read2st64_b64 v[34:37], v61 offset0:74 offset1:75
	s_cmp_gt_i32 s15, 2
	s_cselect_b64 vcc, -1, 0
	s_cmp_gt_i32 s15, 1
	s_waitcnt lgkmcnt(0)
	v_pk_mul_f32 v[38:39], v[36:37], v[38:39]
	s_nop 0
	v_cndmask_b32_e32 v39, 1.0, v39, vcc
	v_cndmask_b32_e32 v38, 1.0, v38, vcc
	v_pk_mul_f32 v[38:39], v[34:35], v[38:39]
	s_cselect_b64 vcc, -1, 0
	v_cndmask_b32_e32 v123, 1.0, v39, vcc
	v_cndmask_b32_e32 v122, 1.0, v38, vcc
	ds_read2st64_b64 v[38:41], v61 offset0:72 offset1:73
	s_cmp_gt_i32 s15, 0
	s_cselect_b64 vcc, -1, 0
	s_cmp_gt_i32 s15, -1
	s_waitcnt lgkmcnt(0)
	v_pk_mul_f32 v[122:123], v[40:41], v[122:123]
	s_nop 0
	v_cndmask_b32_e32 v123, 1.0, v123, vcc
	v_cndmask_b32_e32 v122, 1.0, v122, vcc
	v_pk_mul_f32 v[122:123], v[38:39], v[122:123]
	s_cselect_b64 vcc, -1, 0
	v_cndmask_b32_e32 v123, 1.0, v123, vcc
	v_cndmask_b32_e32 v122, 1.0, v122, vcc
	v_pk_mul_f32 v[118:119], v[120:121], v[122:123]
	v_rcp_f32_e32 v120, v117
	v_rcp_f32_e32 v121, v124
	v_max_f32_e32 v117, 0x2081cea, v86
	s_lshl_b32 s15, s15, 4
	s_cmp_lt_u32 s1, 64
	v_pk_mul_f32 v[118:119], v[120:121], v[118:119]
	v_max_f32_e32 v120, 0x2081cea, v87
	v_pk_mul_f32 v[86:87], v[88:89], v[122:123]
	v_rcp_f32_e32 v88, v117
	v_rcp_f32_e32 v89, v120
	s_nop 0
	v_pk_mul_f32 v[86:87], v[88:89], v[86:87]
	v_max_f32_e32 v88, 0x2081cea, v82
	v_max_f32_e32 v89, 0x2081cea, v83
	v_pk_mul_f32 v[82:83], v[84:85], v[122:123]
	v_rcp_f32_e32 v84, v88
	v_rcp_f32_e32 v85, v89
	s_nop 0
	v_pk_mul_f32 v[82:83], v[84:85], v[82:83]
	v_max_f32_e32 v84, 0x2081cea, v78
	v_max_f32_e32 v85, 0x2081cea, v79
	v_pk_mul_f32 v[78:79], v[80:81], v[122:123]
	v_rcp_f32_e32 v80, v84
	v_rcp_f32_e32 v81, v85
	s_nop 0
	v_pk_mul_f32 v[78:79], v[80:81], v[78:79]
	v_max_f32_e32 v80, 0x2081cea, v74
	v_max_f32_e32 v81, 0x2081cea, v75
	v_pk_mul_f32 v[74:75], v[76:77], v[122:123]
	v_rcp_f32_e32 v76, v80
	v_rcp_f32_e32 v77, v81
	s_nop 0
	v_pk_mul_f32 v[74:75], v[76:77], v[74:75]
	v_max_f32_e32 v76, 0x2081cea, v70
	v_max_f32_e32 v77, 0x2081cea, v71
	v_pk_mul_f32 v[70:71], v[72:73], v[122:123]
	v_rcp_f32_e32 v72, v76
	v_rcp_f32_e32 v73, v77
	s_nop 0
	v_pk_mul_f32 v[70:71], v[72:73], v[70:71]
	v_max_f32_e32 v72, 0x2081cea, v66
	v_max_f32_e32 v73, 0x2081cea, v67
	v_pk_mul_f32 v[66:67], v[68:69], v[122:123]
	v_rcp_f32_e32 v68, v72
	v_rcp_f32_e32 v69, v73
	s_nop 0
	v_pk_mul_f32 v[68:69], v[68:69], v[66:67]
	v_max_f32_e32 v66, 0x2081cea, v62
	v_max_f32_e32 v67, 0x2081cea, v63
	v_pk_mul_f32 v[62:63], v[64:65], v[122:123]
	v_rcp_f32_e32 v64, v66
	v_rcp_f32_e32 v65, v67
	v_cvt_pk_bf16_f32 v66, v119, v87
	v_cvt_pk_bf16_f32 v67, v83, v79
	v_pk_mul_f32 v[72:73], v[64:65], v[62:63]
	v_cvt_pk_bf16_f32 v64, v74, v70
	v_mul_u32_u24_e32 v70, 0x118, v116
	v_cvt_pk_bf16_f32 v62, v118, v86
	v_cvt_pk_bf16_f32 v63, v82, v78
	v_cvt_pk_bf16_f32 v65, v68, v72
	v_add3_u32 v61, v61, v70, s15
	v_cvt_pk_bf16_f32 v68, v75, v71
	v_cvt_pk_bf16_f32 v69, v69, v73
	ds_write_b128 v61, v[62:65] offset:18432
	ds_write_b128 v61, v[66:69] offset:18576
	s_cbranch_scc1 .LBB0_306
	s_ashr_i32 s1, s0, 31
	s_ashr_i32 s15, s14, 31
	s_mov_b64 s[16:17], 0

; #define LAS __attribute__((address_space(3)))
; __device__ __forceinline__ void ret_local_item(const Ctx& X, bf16* H, int it, LocRegs<true>& R, bool has_next) {
;     ...
;     for (int dir = 0; dir < 2; ++dir) { bf16* Sp = St + ((size_t)(chain + dir) * RNCH + n) * 128 * 64; const lptr UT = X.lds + R1_END + dir * 128 * 144;
; #pragma unroll
;         for (int p = 0; p < 2; ++p) { const int idx = X.tid + NTHR * p, row = idx >> 3, c8 = idx & 7; *(v4u*)(Sp + (size_t)row * 64 + 8 * c8) = *(const LAS v4u*)(UT + row * 144 + c8 * 16); } }
.LBB0_310:
	s_or_b64 exec, exec, s[18:19]
	v_lshlrev_b64 v[30:31], 14, v[30:31]
	s_waitcnt lgkmcnt(0)
	s_barrier
	s_nop 2
	ds_read_b128 v[40:43], v222
	ds_read_b128 v[44:47], v223
	ds_read_b128 v[116:119], v224
	v_lshl_add_u64 v[32:33], s[12:13], 0, v[30:31]
	v_lshlrev_b64 v[28:29], 20, v[28:29]
	v_lshl_add_u64 v[34:35], v[32:33], 0, v[28:29]
	v_lshlrev_b64 v[38:39], 7, v[66:67]
	v_lshl_add_u64 v[36:37], v[34:35], 0, v[38:39]
	v_mov_b32_e32 v79, v159
	v_lshl_add_u64 v[36:37], v[36:37], 0, v[78:79]
	s_waitcnt lgkmcnt(2)
	global_store_dwordx4 v[36:37], v[40:43], off
	v_lshl_add_u64 v[34:35], v[34:35], 0, v[70:71]
	v_lshl_add_u64 v[34:35], v[34:35], 0, v[78:79]
	v_lshlrev_b64 v[26:27], 20, v[26:27]
	s_andn2_b64 vcc, exec, s[14:15]
	s_waitcnt lgkmcnt(1)
	global_store_dwordx4 v[34:35], v[44:47], off
	v_lshl_add_u64 v[30:31], v[32:33], 0, v[26:27]
	ds_read_b128 v[26:29], v225
	v_lshl_add_u64 v[32:33], v[30:31], 0, v[38:39]
	v_lshl_add_u64 v[32:33], v[32:33], 0, v[78:79]
	v_lshl_add_u64 v[30:31], v[30:31], 0, v[70:71]
	v_lshl_add_u64 v[30:31], v[30:31], 0, v[78:79]
	s_waitcnt lgkmcnt(1)
	global_store_dwordx4 v[32:33], v[116:119], off
	s_waitcnt lgkmcnt(0)
	global_store_dwordx4 v[30:31], v[26:29], off
	s_waitcnt lgkmcnt(0)
	s_barrier
	s_cbranch_vccz .LBB0_323

; #define LAS __attribute__((address_space(3)))
; __device__ __forceinline__ float bf2f(unsigned h) { return __uint_as_float(h << 16); }
; __device__ __forceinline__ void ret_local_item(const Ctx& X, bf16* H, int it, LocRegs<true>& R, bool has_next) {
;     ...
;         if (active) {
; #pragma unroll
;             for (int ii = 0; ii < 16; ++ii) { const int rr = 16 * rq + ii; const float c_ = cs[rr * 32 + k2], s_ = sn[rr * 32 + k2];
;                 const float q1 = bf2f(*(const LAS unsigned short*)(rawq + (rr * 64 + k2) * 2)), q2 = bf2f(*(const LAS unsigned short*)(rawq + (rr * 64 + 32 + k2) * 2));
;                 const float k1 = bf2f(*(const LAS unsigned short*)(rawk + (rr * 64 + k2) * 2)), k2v = bf2f(*(const LAS unsigned short*)(rawk + (rr * 64 + 32 + k2) * 2));
;                 qr[ii] = (k < 32) ? (q1 * c_ - q2 * s_) : (q1 * s_ + q2 * c_); kr[ii] = 0.125f * ((k < 32) ? (k1 * c_ - k2v * s_) : (k1 * s_ + k2v * c_)); } }
.LBB0_315:
	s_waitcnt lgkmcnt(0)
	s_barrier
	s_and_saveexec_b64 s[0:1], s[40:41]
	s_cbranch_execz .LBB0_317
	ds_read2st64_b32 v[228:229], v123 offset0:208 offset1:240
	ds_read2st64_b32 v[86:87], v125 offset0:208 offset1:240
	ds_read_u16 v232, v167 offset:36864
	ds_read_u16 v236, v166 offset:36864
	s_waitcnt lgkmcnt(3)
	v_mov_b32_e32 v91, v228
	s_waitcnt lgkmcnt(2)
	v_mov_b32_e32 v90, v86
	s_waitcnt lgkmcnt(1)
	v_lshlrev_b32_e32 v82, 16, v232
	ds_read_u16 v240, v167 offset:36928
	s_waitcnt lgkmcnt(1)
	v_lshlrev_b32_e32 v83, 16, v236
	ds_read_u16 v232, v166 offset:36928
	v_mov_b32_e32 v92, v87
	v_mov_b32_e32 v93, v229
	s_waitcnt lgkmcnt(1)
	v_lshlrev_b32_e32 v88, 16, v240
	ds_read_u16 v236, v166 offset:45056
	s_waitcnt lgkmcnt(1)
	v_lshlrev_b32_e32 v89, 16, v232
	ds_read_u16 v240, v167 offset:45056
	v_pk_mul_f32 v[94:95], v[92:93], v[88:89]
	v_pk_mul_f32 v[88:89], v[90:91], v[88:89]
	v_pk_fma_f32 v[94:95], v[90:91], v[82:83], v[94:95] neg_lo:[0,0,1] neg_hi:[0,0,1]
	v_pk_fma_f32 v[82:83], v[92:93], v[82:83], v[88:89]
	s_waitcnt lgkmcnt(0)
	v_lshlrev_b32_e32 v89, 16, v240
	ds_read_u16 v232, v166 offset:45120
	v_lshlrev_b32_e32 v88, 16, v236
	ds_read_u16 v240, v167 offset:45120
	v_mov_b32_e32 v92, v228
	v_mov_b32_e32 v93, v86
	ds_read2st64_b32 v[236:237], v127 offset0:208 offset1:240
	v_mov_b32_e32 v86, v229
	s_waitcnt lgkmcnt(2)
	v_lshlrev_b32_e32 v90, 16, v232
	s_waitcnt lgkmcnt(1)
	v_lshlrev_b32_e32 v91, 16, v240
	v_pk_mul_f32 v[84:85], v[86:87], v[90:91]
	v_pk_mul_f32 v[90:91], v[92:93], v[90:91]
	v_pk_fma_f32 v[84:85], v[92:93], v[88:89], v[84:85] neg_lo:[0,0,1] neg_hi:[0,0,1]
	v_pk_fma_f32 v[86:87], v[86:87], v[88:89], v[90:91]
	ds_read2st64_b32 v[90:91], v129 offset0:208 offset1:240
	ds_read_u16 v228, v169 offset:36864
	ds_read_u16 v232, v168 offset:36864
	v_cndmask_b32_e64 v85, v87, v85, s[42:43]
	v_cndmask_b32_e64 v84, v86, v84, s[42:43]
	v_cndmask_b32_e64 v83, v83, v95, s[42:43]
	s_waitcnt lgkmcnt(1)
	v_lshlrev_b32_e32 v86, 16, v228
	ds_read_u16 v240, v169 offset:36928
	s_waitcnt lgkmcnt(1)
	v_lshlrev_b32_e32 v87, 16, v232
	ds_read_u16 v228, v168 offset:36928
	v_cndmask_b32_e64 v82, v82, v94, s[42:43]
	v_mov_b32_e32 v94, v90
	v_mov_b32_e32 v95, v236
	s_waitcnt lgkmcnt(1)
	v_lshlrev_b32_e32 v92, 16, v240
	ds_read_u16 v232, v168 offset:45056
	s_waitcnt lgkmcnt(1)
	v_lshlrev_b32_e32 v93, 16, v228
	ds_read_u16 v240, v169 offset:45056
	v_mov_b32_e32 v96, v91
	v_mov_b32_e32 v97, v237
	v_pk_mul_f32 v[98:99], v[96:97], v[92:93]
	v_pk_mul_f32 v[92:93], v[94:95], v[92:93]
	v_pk_fma_f32 v[98:99], v[94:95], v[86:87], v[98:99] neg_lo:[0,0,1] neg_hi:[0,0,1]
	v_pk_fma_f32 v[86:87], v[96:97], v[86:87], v[92:93]
	s_waitcnt lgkmcnt(0)
	v_lshlrev_b32_e32 v93, 16, v240
	ds_read_u16 v228, v168 offset:45120
	v_lshlrev_b32_e32 v92, 16, v232
	ds_read_u16 v240, v169 offset:45120
	v_mov_b32_e32 v96, v236
	v_mov_b32_e32 v97, v90
	ds_read2st64_b32 v[232:233], v131 offset0:208 offset1:240
	v_mov_b32_e32 v90, v237
	s_waitcnt lgkmcnt(2)
	v_lshlrev_b32_e32 v94, 16, v228
	s_waitcnt lgkmcnt(1)
	v_lshlrev_b32_e32 v95, 16, v240
	v_pk_mul_f32 v[88:89], v[90:91], v[94:95]
	v_pk_mul_f32 v[94:95], v[96:97], v[94:95]
	v_pk_fma_f32 v[88:89], v[96:97], v[92:93], v[88:89] neg_lo:[0,0,1] neg_hi:[0,0,1]
	v_pk_fma_f32 v[90:91], v[90:91], v[92:93], v[94:95]
	ds_read2st64_b32 v[94:95], v133 offset0:208 offset1:240
	ds_read_u16 v236, v171 offset:36864
	ds_read_u16 v228, v170 offset:36864
	v_cndmask_b32_e64 v89, v91, v89, s[42:43]
	v_cndmask_b32_e64 v88, v90, v88, s[42:43]
	v_cndmask_b32_e64 v87, v87, v99, s[42:43]
	s_waitcnt lgkmcnt(1)
	v_lshlrev_b32_e32 v90, 16, v236
	ds_read_u16 v240, v171 offset:36928
	s_waitcnt lgkmcnt(1)
	v_lshlrev_b32_e32 v91, 16, v228
	ds_read_u16 v236, v170 offset:36928
	v_cndmask_b32_e64 v86, v86, v98, s[42:43]
	v_mov_b32_e32 v98, v94
	v_mov_b32_e32 v99, v232
	s_waitcnt lgkmcnt(1)
	v_lshlrev_b32_e32 v96, 16, v240
	ds_read_u16 v228, v170 offset:45056
	s_waitcnt lgkmcnt(1)
	v_lshlrev_b32_e32 v97, 16, v236
	ds_read_u16 v240, v171 offset:45056
	v_mov_b32_e32 v100, v95
	v_mov_b32_e32 v101, v233
	v_pk_mul_f32 v[102:103], v[100:101], v[96:97]
	v_pk_mul_f32 v[96:97], v[98:99], v[96:97]
	v_pk_fma_f32 v[102:103], v[98:99], v[90:91], v[102:103] neg_lo:[0,0,1] neg_hi:[0,0,1]
	v_pk_fma_f32 v[90:91], v[100:101], v[90:91], v[96:97]
	s_waitcnt lgkmcnt(0)
	v_lshlrev_b32_e32 v97, 16, v240
	ds_read_u16 v236, v170 offset:45120
	v_lshlrev_b32_e32 v96, 16, v228
	ds_read_u16 v240, v171 offset:45120
	v_mov_b32_e32 v100, v232
	v_mov_b32_e32 v101, v94
	ds_read2st64_b32 v[228:229], v135 offset0:208 offset1:240
	v_mov_b32_e32 v94, v233
	s_waitcnt lgkmcnt(2)
	v_lshlrev_b32_e32 v98, 16, v236
	s_waitcnt lgkmcnt(1)
	v_lshlrev_b32_e32 v99, 16, v240
	v_pk_mul_f32 v[92:93], v[94:95], v[98:99]
	v_pk_mul_f32 v[98:99], v[100:101], v[98:99]
	v_pk_fma_f32 v[92:93], v[100:101], v[96:97], v[92:93] neg_lo:[0,0,1] neg_hi:[0,0,1]
	v_pk_fma_f32 v[94:95], v[94:95], v[96:97], v[98:99]
	ds_read2st64_b32 v[98:99], v137 offset0:208 offset1:240
	ds_read_u16 v232, v173 offset:36864
	ds_read_u16 v236, v172 offset:36864
	v_cndmask_b32_e64 v93, v95, v93, s[42:43]
	v_cndmask_b32_e64 v92, v94, v92, s[42:43]
	v_cndmask_b32_e64 v91, v91, v103, s[42:43]
	s_waitcnt lgkmcnt(1)
	v_lshlrev_b32_e32 v94, 16, v232
	ds_read_u16 v240, v173 offset:36928
	s_waitcnt lgkmcnt(1)
	v_lshlrev_b32_e32 v95, 16, v236
	ds_read_u16 v232, v172 offset:36928
	v_cndmask_b32_e64 v90, v90, v102, s[42:43]
	v_mov_b32_e32 v102, v98
	v_mov_b32_e32 v103, v228
	s_waitcnt lgkmcnt(1)
	v_lshlrev_b32_e32 v100, 16, v240
	ds_read_u16 v236, v172 offset:45056
	s_waitcnt lgkmcnt(1)
; #define LAS __attribute__((address_space(3)))
; __device__ __forceinline__ float bf2f(unsigned h) { return __uint_as_float(h << 16); }
; __device__ __forceinline__ void ret_local_item(const Ctx& X, bf16* H, int it, LocRegs<true>& R, bool has_next) {
;     ...
;         if (active) {
; #pragma unroll
;             for (int ii = 0; ii < 16; ++ii) { const int rr = 16 * rq + ii; const float c_ = cs[rr * 32 + k2], s_ = sn[rr * 32 + k2];
;                 const float q1 = bf2f(*(const LAS unsigned short*)(rawq + (rr * 64 + k2) * 2)), q2 = bf2f(*(const LAS unsigned short*)(rawq + (rr * 64 + 32 + k2) * 2));
;                 const float k1 = bf2f(*(const LAS unsigned short*)(rawk + (rr * 64 + k2) * 2)), k2v = bf2f(*(const LAS unsigned short*)(rawk + (rr * 64 + 32 + k2) * 2));
;                 qr[ii] = (k < 32) ? (q1 * c_ - q2 * s_) : (q1 * s_ + q2 * c_); kr[ii] = 0.125f * ((k < 32) ? (k1 * c_ - k2v * s_) : (k1 * s_ + k2v * c_)); } }
	v_lshlrev_b32_e32 v101, 16, v232
	ds_read_u16 v240, v173 offset:45056
	v_mov_b32_e32 v104, v99
	v_mov_b32_e32 v105, v229
	v_pk_mul_f32 v[106:107], v[104:105], v[100:101]
	v_pk_mul_f32 v[100:101], v[102:103], v[100:101]
	v_pk_fma_f32 v[106:107], v[102:103], v[94:95], v[106:107] neg_lo:[0,0,1] neg_hi:[0,0,1]
	v_pk_fma_f32 v[94:95], v[104:105], v[94:95], v[100:101]
	s_waitcnt lgkmcnt(0)
	v_lshlrev_b32_e32 v101, 16, v240
	ds_read_u16 v232, v172 offset:45120
	v_lshlrev_b32_e32 v100, 16, v236
	ds_read_u16 v240, v173 offset:45120
	v_mov_b32_e32 v104, v228
	v_mov_b32_e32 v105, v98
	ds_read2st64_b32 v[236:237], v139 offset0:208 offset1:240
	v_mov_b32_e32 v98, v229
	s_waitcnt lgkmcnt(2)
	v_lshlrev_b32_e32 v102, 16, v232
	s_waitcnt lgkmcnt(1)
	v_lshlrev_b32_e32 v103, 16, v240
	v_pk_mul_f32 v[96:97], v[98:99], v[102:103]
	v_pk_mul_f32 v[102:103], v[104:105], v[102:103]
	v_pk_fma_f32 v[96:97], v[104:105], v[100:101], v[96:97] neg_lo:[0,0,1] neg_hi:[0,0,1]
	v_pk_fma_f32 v[98:99], v[98:99], v[100:101], v[102:103]
	ds_read2st64_b32 v[102:103], v141 offset0:208 offset1:240
	ds_read_u16 v228, v175 offset:36864
	ds_read_u16 v232, v174 offset:36864
	v_cndmask_b32_e64 v97, v99, v97, s[42:43]
	v_cndmask_b32_e64 v96, v98, v96, s[42:43]
	v_cndmask_b32_e64 v95, v95, v107, s[42:43]
	s_waitcnt lgkmcnt(1)
	v_lshlrev_b32_e32 v98, 16, v228
	ds_read_u16 v240, v175 offset:36928
	s_waitcnt lgkmcnt(1)
	v_lshlrev_b32_e32 v99, 16, v232
	ds_read_u16 v228, v174 offset:36928
	v_cndmask_b32_e64 v94, v94, v106, s[42:43]
	v_mov_b32_e32 v106, v102
	v_mov_b32_e32 v107, v236
	s_waitcnt lgkmcnt(1)
	v_lshlrev_b32_e32 v104, 16, v240
	ds_read_u16 v232, v174 offset:45056
	s_waitcnt lgkmcnt(1)
	v_lshlrev_b32_e32 v105, 16, v228
	ds_read_u16 v240, v175 offset:45056
	v_mov_b32_e32 v108, v103
	v_mov_b32_e32 v109, v237
	v_pk_mul_f32 v[110:111], v[108:109], v[104:105]
	v_pk_mul_f32 v[104:105], v[106:107], v[104:105]
	v_pk_fma_f32 v[110:111], v[106:107], v[98:99], v[110:111] neg_lo:[0,0,1] neg_hi:[0,0,1]
	v_pk_fma_f32 v[98:99], v[108:109], v[98:99], v[104:105]
	s_waitcnt lgkmcnt(0)
	v_lshlrev_b32_e32 v105, 16, v240
	ds_read_u16 v228, v174 offset:45120
	v_lshlrev_b32_e32 v104, 16, v232
	ds_read_u16 v240, v175 offset:45120
	v_mov_b32_e32 v108, v236
	v_mov_b32_e32 v109, v102
	ds_read2st64_b32 v[232:233], v143 offset0:208 offset1:240
	v_mov_b32_e32 v102, v237
	s_waitcnt lgkmcnt(2)
	v_lshlrev_b32_e32 v106, 16, v228
	s_waitcnt lgkmcnt(1)
	v_lshlrev_b32_e32 v107, 16, v240
	v_pk_mul_f32 v[100:101], v[102:103], v[106:107]
	v_pk_mul_f32 v[106:107], v[108:109], v[106:107]
	v_pk_fma_f32 v[100:101], v[108:109], v[104:105], v[100:101] neg_lo:[0,0,1] neg_hi:[0,0,1]
	v_pk_fma_f32 v[102:103], v[102:103], v[104:105], v[106:107]
	ds_read2st64_b32 v[106:107], v145 offset0:208 offset1:240
	ds_read_u16 v236, v177 offset:36864
	ds_read_u16 v228, v176 offset:36864
	v_cndmask_b32_e64 v101, v103, v101, s[42:43]
	v_cndmask_b32_e64 v100, v102, v100, s[42:43]
	v_cndmask_b32_e64 v99, v99, v111, s[42:43]
	s_waitcnt lgkmcnt(1)
	v_lshlrev_b32_e32 v102, 16, v236
	ds_read_u16 v240, v177 offset:36928
	s_waitcnt lgkmcnt(1)
	v_lshlrev_b32_e32 v103, 16, v228
	ds_read_u16 v236, v176 offset:36928
	v_cndmask_b32_e64 v98, v98, v110, s[42:43]
	v_mov_b32_e32 v110, v106
	v_mov_b32_e32 v111, v232
	s_waitcnt lgkmcnt(1)
	v_lshlrev_b32_e32 v108, 16, v240
	ds_read_u16 v228, v176 offset:45056
	s_waitcnt lgkmcnt(1)
	v_lshlrev_b32_e32 v109, 16, v236
	ds_read_u16 v240, v177 offset:45056
	v_mov_b32_e32 v112, v107
	v_mov_b32_e32 v113, v233
	v_pk_mul_f32 v[114:115], v[112:113], v[108:109]
	v_pk_mul_f32 v[108:109], v[110:111], v[108:109]
	v_pk_fma_f32 v[114:115], v[110:111], v[102:103], v[114:115] neg_lo:[0,0,1] neg_hi:[0,0,1]
	v_pk_fma_f32 v[102:103], v[112:113], v[102:103], v[108:109]
	s_waitcnt lgkmcnt(0)
	v_lshlrev_b32_e32 v109, 16, v240
	ds_read_u16 v236, v176 offset:45120
	v_lshlrev_b32_e32 v108, 16, v228
	ds_read_u16 v240, v177 offset:45120
	v_mov_b32_e32 v112, v232
	v_mov_b32_e32 v113, v106
	ds_read2st64_b32 v[228:229], v147 offset0:208 offset1:240
	v_mov_b32_e32 v106, v233
	s_waitcnt lgkmcnt(2)
	v_lshlrev_b32_e32 v110, 16, v236
	s_waitcnt lgkmcnt(1)
; #define LAS __attribute__((address_space(3)))
; __device__ __forceinline__ float bf2f(unsigned h) { return __uint_as_float(h << 16); }
; __device__ __forceinline__ void ret_local_item(const Ctx& X, bf16* H, int it, LocRegs<true>& R, bool has_next) {
;     ...
;         if (active) {
; #pragma unroll
;             for (int ii = 0; ii < 16; ++ii) { const int rr = 16 * rq + ii; const float c_ = cs[rr * 32 + k2], s_ = sn[rr * 32 + k2];
;                 const float q1 = bf2f(*(const LAS unsigned short*)(rawq + (rr * 64 + k2) * 2)), q2 = bf2f(*(const LAS unsigned short*)(rawq + (rr * 64 + 32 + k2) * 2));
;                 const float k1 = bf2f(*(const LAS unsigned short*)(rawk + (rr * 64 + k2) * 2)), k2v = bf2f(*(const LAS unsigned short*)(rawk + (rr * 64 + 32 + k2) * 2));
;                 qr[ii] = (k < 32) ? (q1 * c_ - q2 * s_) : (q1 * s_ + q2 * c_); kr[ii] = 0.125f * ((k < 32) ? (k1 * c_ - k2v * s_) : (k1 * s_ + k2v * c_)); } }
	v_lshlrev_b32_e32 v111, 16, v240
	v_pk_mul_f32 v[104:105], v[106:107], v[110:111]
	v_pk_mul_f32 v[110:111], v[112:113], v[110:111]
	v_pk_fma_f32 v[104:105], v[112:113], v[108:109], v[104:105] neg_lo:[0,0,1] neg_hi:[0,0,1]
	v_pk_fma_f32 v[106:107], v[106:107], v[108:109], v[110:111]
	ds_read2st64_b32 v[110:111], v149 offset0:208 offset1:240
	ds_read_u16 v232, v179 offset:36864
	ds_read_u16 v236, v178 offset:36864
	v_cndmask_b32_e64 v105, v107, v105, s[42:43]
	v_cndmask_b32_e64 v104, v106, v104, s[42:43]
	v_cndmask_b32_e64 v103, v103, v115, s[42:43]
	s_waitcnt lgkmcnt(1)
	v_lshlrev_b32_e32 v106, 16, v232
	ds_read_u16 v240, v179 offset:36928
	s_waitcnt lgkmcnt(1)
	v_lshlrev_b32_e32 v107, 16, v236
	ds_read_u16 v232, v178 offset:36928
	v_cndmask_b32_e64 v102, v102, v114, s[42:43]
	v_mov_b32_e32 v114, v110
	v_mov_b32_e32 v115, v228
	s_waitcnt lgkmcnt(1)
	v_lshlrev_b32_e32 v112, 16, v240
	ds_read_u16 v236, v178 offset:45056
	s_waitcnt lgkmcnt(1)
	v_lshlrev_b32_e32 v113, 16, v232
	ds_read_u16 v240, v179 offset:45056
	v_mov_b32_e32 v116, v111
	v_mov_b32_e32 v117, v229
	v_pk_mul_f32 v[118:119], v[116:117], v[112:113]
	v_pk_mul_f32 v[112:113], v[114:115], v[112:113]
	v_pk_fma_f32 v[118:119], v[114:115], v[106:107], v[118:119] neg_lo:[0,0,1] neg_hi:[0,0,1]
	v_pk_fma_f32 v[106:107], v[116:117], v[106:107], v[112:113]
	s_waitcnt lgkmcnt(0)
	v_lshlrev_b32_e32 v113, 16, v240
	ds_read_u16 v232, v178 offset:45120
	v_lshlrev_b32_e32 v112, 16, v236
	ds_read_u16 v240, v179 offset:45120
	v_mov_b32_e32 v116, v228
	v_mov_b32_e32 v117, v110
	ds_read2st64_b32 v[236:237], v151 offset0:208 offset1:240
	v_mov_b32_e32 v110, v229
	s_waitcnt lgkmcnt(2)
	v_lshlrev_b32_e32 v114, 16, v232
	s_waitcnt lgkmcnt(1)
	v_lshlrev_b32_e32 v115, 16, v240
	v_pk_mul_f32 v[108:109], v[110:111], v[114:115]
	v_pk_mul_f32 v[114:115], v[116:117], v[114:115]
	v_pk_fma_f32 v[108:109], v[116:117], v[112:113], v[108:109] neg_lo:[0,0,1] neg_hi:[0,0,1]
	v_pk_fma_f32 v[110:111], v[110:111], v[112:113], v[114:115]
	ds_read2st64_b32 v[114:115], v153 offset0:208 offset1:240
	ds_read_u16 v228, v181 offset:36864
	ds_read_u16 v232, v180 offset:36864
	v_cndmask_b32_e64 v109, v111, v109, s[42:43]
	v_cndmask_b32_e64 v108, v110, v108, s[42:43]
	v_cndmask_b32_e64 v107, v107, v119, s[42:43]
	s_waitcnt lgkmcnt(1)
	v_lshlrev_b32_e32 v110, 16, v228
	ds_read_u16 v240, v181 offset:36928
	s_waitcnt lgkmcnt(1)
	v_lshlrev_b32_e32 v111, 16, v232
	ds_read_u16 v228, v180 offset:36928
	v_cndmask_b32_e64 v106, v106, v118, s[42:43]
	v_mov_b32_e32 v118, v114
	v_mov_b32_e32 v119, v236
	s_waitcnt lgkmcnt(1)
	v_lshlrev_b32_e32 v116, 16, v240
	ds_read_u16 v232, v180 offset:45056
	s_waitcnt lgkmcnt(1)
	v_lshlrev_b32_e32 v117, 16, v228
	ds_read_u16 v240, v181 offset:45056
	v_mov_b32_e32 v162, v115
	v_mov_b32_e32 v163, v237
	v_pk_mul_f32 v[164:165], v[162:163], v[116:117]
	v_pk_mul_f32 v[116:117], v[118:119], v[116:117]
	v_pk_fma_f32 v[164:165], v[118:119], v[110:111], v[164:165] neg_lo:[0,0,1] neg_hi:[0,0,1]
	v_pk_fma_f32 v[110:111], v[162:163], v[110:111], v[116:117]
	s_waitcnt lgkmcnt(0)
	v_lshlrev_b32_e32 v117, 16, v240
	ds_read_u16 v228, v180 offset:45120
	v_lshlrev_b32_e32 v116, 16, v232
	ds_read_u16 v240, v181 offset:45120
	v_mov_b32_e32 v162, v236
	v_mov_b32_e32 v163, v114
	v_mov_b32_e32 v114, v237
	s_waitcnt lgkmcnt(1)
	v_lshlrev_b32_e32 v118, 16, v228
	s_waitcnt lgkmcnt(0)
	v_lshlrev_b32_e32 v119, 16, v240
	v_pk_mul_f32 v[112:113], v[114:115], v[118:119]
	v_pk_mul_f32 v[118:119], v[162:163], v[118:119]
	v_pk_fma_f32 v[112:113], v[162:163], v[116:117], v[112:113] neg_lo:[0,0,1] neg_hi:[0,0,1]
	v_pk_fma_f32 v[114:115], v[114:115], v[116:117], v[118:119]
	v_pk_mul_f32 v[84:85], v[84:85], s[26:27] op_sel_hi:[1,0]
	v_cndmask_b32_e64 v113, v115, v113, s[42:43]
	v_cndmask_b32_e64 v112, v114, v112, s[42:43]
	v_pk_mul_f32 v[88:89], v[88:89], s[26:27] op_sel_hi:[1,0]
	v_pk_mul_f32 v[92:93], v[92:93], s[26:27] op_sel_hi:[1,0]
	v_pk_mul_f32 v[96:97], v[96:97], s[26:27] op_sel_hi:[1,0]
	v_pk_mul_f32 v[100:101], v[100:101], s[26:27] op_sel_hi:[1,0]
	v_pk_mul_f32 v[104:105], v[104:105], s[26:27] op_sel_hi:[1,0]
	v_pk_mul_f32 v[108:109], v[108:109], s[26:27] op_sel_hi:[1,0]
	v_cndmask_b32_e64 v111, v111, v165, s[42:43]
	v_cndmask_b32_e64 v110, v110, v164, s[42:43]
	v_pk_mul_f32 v[112:113], v[112:113], s[26:27] op_sel_hi:[1,0]
	s_waitcnt lgkmcnt(0)

; #define LAS __attribute__((address_space(3)))
; __device__ __forceinline__ unsigned pk2(float lo, float hi) { return pg8::cvt_pk_bf16(lo, hi); }
; #define MFMA16(a, b, c) __builtin_amdgcn_mfma_f32_16x16x32_bf16((a), (b), (c), 0, 0, 0)
; template <int DK, bool RET, int DIR>
; __device__ __forceinline__ void gla_out_dir(const Ctx& X, int chain, int n, f32x2v lb, const unsigned char* St, f32x4 (&o)[4], const bf16* H, size_t m0, int zbcol) {
;     ...
;     RawRegs<128> zbr; if (!RET && DIR == 0) raw_load<128>(X, H, m0, zbcol, zbr);
; #pragma unroll
;     for (int bi = 0; bi < 2; ++bi) { const int blk = 2 * X.wave + bi, I = blk >> 2, J = blk & 3; const int sI = DIR ? 3 - I : I, sJ = DIR ? 3 - J : J;
;         v2u w; w.x = 0u; w.y = 0u;
;         if (sJ <= sI) { const bool same = (sI >> 1) == (sJ >> 1); const lptr KS = same ? KD : KH; const int krow = same ? 16 * J + fr : (DIR ? 16 * J + fr - 32 : 16 * J + fr);
;             f32x4 acc = (f32x4){0.f, 0.f, 0.f, 0.f};
; #pragma unroll
;             for (int ks = 0; ks < DK / 32; ++ks) { const bf16x8 a = ldsfrag(KS, krow, SQ, 32 * ks + 8 * fq); const bf16x8 bb = ldsfrag(Q0, 16 * I + fr, SQ, 32 * ks + 8 * fq); acc = MFMA16(a, bb, acc); }
;             if (sI == sJ) {
; #pragma unroll
;                 for (int j = 0; j < 4; ++j) { const int jl = 4 * fq + j; const bool keep = DIR ? (jl >= fr) : (jl <= fr); if (!keep) acc[j] = 0.f; } }
;             w.x = pk2(acc[0], acc[1]); w.y = pk2(acc[2], acc[3]); }
;         *(LAS v2u*)(AM + (16 * I + fr) * 144 + (16 * J + 4 * fq) * 2) = w; }
.LBB0_517:
	s_lshl_b32 s60, s84, 13
	s_lshl_b32 s61, s83, 13
	s_sub_i32 s60, s60, s61
	s_add_i32 s68, s80, s60
	s_ashr_i32 s69, s68, 31
	s_add_i32 s60, s14, 0x900
	v_add_u32_e32 v28, s60, v47
	v_lshrrev_b32_e32 v158, 7, v28
	v_lshl_add_u64 v[26:27], s[68:69], 0, v[44:45]
	v_lshlrev_b64 v[28:29], 22, v[158:159]
	v_add_u32_e32 v30, s60, v112
	v_lshl_add_u64 v[28:29], s[24:25], 0, v[28:29]
	v_lshlrev_b64 v[26:27], 8, v[26:27]
	v_lshrrev_b32_e32 v158, 7, v30
	v_lshl_add_u64 v[26:27], v[28:29], 0, v[26:27]
	v_lshl_add_u64 v[28:29], s[68:69], 0, v[48:49]
	v_lshlrev_b64 v[30:31], 22, v[158:159]
	v_lshl_add_u64 v[30:31], s[24:25], 0, v[30:31]
	v_lshlrev_b64 v[28:29], 8, v[28:29]
	v_mov_b32_e32 v35, v159
	v_lshl_add_u64 v[28:29], v[30:31], 0, v[28:29]
	v_mov_b32_e32 v61, v159
	s_waitcnt lgkmcnt(0)
	s_barrier
	v_lshl_add_u64 v[26:27], v[26:27], 0, v[34:35]
	v_lshl_add_u64 v[30:31], v[28:29], 0, v[60:61]
	global_load_dwordx4 v[26:29], v[26:27], off
	s_nop 0
	global_load_dwordx4 v[30:33], v[30:31], off
	v_mov_b32_e32 v34, 0
	s_andn2_b64 vcc, exec, s[36:37]
	v_mov_b32_e32 v36, 0
	v_mov_b32_e32 v37, 0
	s_cbranch_vccnz .LBB0_519
	s_nop 3
	ds_read_b128 v[76:79], v130
	ds_read_b128 v[80:83], v142
	ds_read_b128 v[84:87], v130 offset:64
	ds_read_b128 v[88:91], v142 offset:64
	ds_read_b128 v[92:95], v130 offset:128
	ds_read_b128 v[96:99], v142 offset:128
	ds_read_b128 v[100:103], v130 offset:192
	ds_read_b128 v[104:107], v142 offset:192
	s_and_b64 s[60:61], s[16:17], s[46:47]
	s_waitcnt lgkmcnt(6)
	v_mfma_f32_16x16x32_bf16 v[36:39], v[76:79], v[80:83], 0
	s_waitcnt lgkmcnt(4)
	v_mfma_f32_16x16x32_bf16 v[36:39], v[84:87], v[88:91], v[36:39]
	s_waitcnt lgkmcnt(2)
	v_mfma_f32_16x16x32_bf16 v[36:39], v[92:95], v[96:99], v[36:39]
	s_waitcnt lgkmcnt(0)
	v_mfma_f32_16x16x32_bf16 v[36:39], v[100:103], v[104:107], v[36:39]
	s_nop 7
	v_cndmask_b32_e64 v38, v38, 0, s[60:61]
	s_and_b64 s[60:61], s[60:61], s[44:45]
	v_cndmask_b32_e64 v37, v37, 0, s[60:61]
	s_and_b64 s[60:61], s[60:61], s[42:43]
	v_cndmask_b32_e64 v35, v39, 0, s[16:17]
	v_cndmask_b32_e64 v36, v36, 0, s[60:61]
	v_cvt_pk_bf16_f32 v36, v36, v37
	v_cvt_pk_bf16_f32 v37, v38, v35
	s_waitcnt lgkmcnt(0)
.LBB0_519:
	s_andn2_b64 vcc, exec, s[38:39]
	v_mov_b32_e32 v35, 0
	s_mov_b64 s[84:85], s[64:65]
	ds_write_b64 v143, v[36:37]
	s_cbranch_vccnz .LBB0_521
	s_nop 3
	ds_read_b128 v[72:75], v131
	ds_read_b128 v[76:79], v142
	ds_read_b128 v[80:83], v131 offset:64
	ds_read_b128 v[84:87], v142 offset:64
	ds_read_b128 v[88:91], v131 offset:128
	ds_read_b128 v[92:95], v142 offset:128
	ds_read_b128 v[96:99], v131 offset:192
	ds_read_b128 v[100:103], v142 offset:192
	s_and_b64 s[60:61], s[22:23], s[46:47]
	s_waitcnt lgkmcnt(6)
	v_mfma_f32_16x16x32_bf16 v[34:37], v[72:75], v[76:79], 0
	s_waitcnt lgkmcnt(4)
	v_mfma_f32_16x16x32_bf16 v[34:37], v[80:83], v[84:87], v[34:37]
	s_waitcnt lgkmcnt(2)
	v_mfma_f32_16x16x32_bf16 v[34:37], v[88:91], v[92:95], v[34:37]
	s_waitcnt lgkmcnt(0)
	v_mfma_f32_16x16x32_bf16 v[34:37], v[96:99], v[100:103], v[34:37]
	s_nop 7
	v_cndmask_b32_e64 v36, v36, 0, s[60:61]
	s_and_b64 s[60:61], s[60:61], s[44:45]
	v_cndmask_b32_e64 v35, v35, 0, s[60:61]
	s_and_b64 s[60:61], s[60:61], s[42:43]
	v_cndmask_b32_e64 v37, v37, 0, s[22:23]
	v_cndmask_b32_e64 v34, v34, 0, s[60:61]
	v_cvt_pk_bf16_f32 v34, v34, v35
	v_cvt_pk_bf16_f32 v35, v36, v37
	s_waitcnt lgkmcnt(0)

; #define LAS __attribute__((address_space(3)))
; template <int DK, bool RET, int DIR>
; __device__ __forceinline__ void gla_out_dir(const Ctx& X, int chain, int n, f32x2v lb, const unsigned char* St, f32x4 (&o)[4], const bf16* H, size_t m0, int zbcol) {
;     ...
;     for (int bi = 0; bi < 2; ++bi) { const int blk = 2 * X.wave + bi, I = blk >> 2, J = blk & 3; const int sI = DIR ? 3 - I : I, sJ = DIR ? 3 - J : J;
;         v2u w; w.x = 0u; w.y = 0u;
;         if (sJ <= sI) { const bool same = (sI >> 1) == (sJ >> 1); const lptr KS = same ? KD : KH; const int krow = same ? 16 * J + fr : (DIR ? 16 * J + fr - 32 : 16 * J + fr);
;             f32x4 acc = (f32x4){0.f, 0.f, 0.f, 0.f};
; #pragma unroll
;             for (int ks = 0; ks < DK / 32; ++ks) { const bf16x8 a = ldsfrag(KS, krow, SQ, 32 * ks + 8 * fq); const bf16x8 bb = ldsfrag(Q0, 16 * I + fr, SQ, 32 * ks + 8 * fq); acc = MFMA16(a, bb, acc); }
;             if (sI == sJ) {
; #pragma unroll
;                 for (int j = 0; j < 4; ++j) { const int jl = 4 * fq + j; const bool keep = DIR ? (jl >= fr) : (jl <= fr); if (!keep) acc[j] = 0.f; } }
;             w.x = pk2(acc[0], acc[1]); w.y = pk2(acc[2], acc[3]); }
;         *(LAS v2u*)(AM + (16 * I + fr) * 144 + (16 * J + 4 * fq) * 2) = w; }
;     BAR_LDS(); SP_END(23);
;     {
;         const int stb = DIR ? 3 - tb : tb; const int r = 16 * tb + fr;
; #pragma unroll
;         for (int ks = 0; ks < 2; ++ks) { const bf16x8 bb = ldsfrag(AM, r, 144, 32 * ks + 8 * fq);
; #pragma unroll
;             for (int vt = 0; vt < 4; ++vt) { const bf16x8 a = vtfrag(VT, 64 * vh + 16 * vt + fr, 144, 32 * ks + 8 * fq); o[vt] = MFMA16(a, bb, o[vt]); } }
;         const lptr QI = (stb >> 1) ? Q1 : Q0; const int qrow = (stb >> 1) ? (DIR ? r : r - 32) : r;
; #pragma unroll
;         for (int ks = 0; ks < DK / 32; ++ks) { const bf16x8 bb = ldsfrag(QI, qrow, SQ, 32 * ks + 8 * fq);
; #pragma unroll
;             for (int vt = 0; vt < 4; ++vt) { const bf16x8 a = ldsfrag(ST, 64 * vh + 16 * vt + fr, 272, 32 * ks + 8 * fq); o[vt] = MFMA16(a, bb, o[vt]); } }
; template <int DK, bool RET>
; __device__ __forceinline__ void gla_out_item(const Ctx& X, const bf16* H, bf16* Y, int l, int r, OutRegs<RET>& R, bool has_next) {
;     ...
;     float s2 = 0.f;
; #pragma unroll
;     for (int t = 0; t < 4; ++t)
; #pragma unroll
;         for (int j = 0; j < 4; ++j) { const float dlt = o[t][j] - mu; s2 += dlt * dlt; }
.LBB0_558:
	s_waitcnt lgkmcnt(0)
	s_barrier
	v_mov_b32_e32 v66, 0
	s_andn2_b64 vcc, exec, s[66:67]
	v_mov_b32_e32 v74, 0
	v_mov_b32_e32 v75, 0
	s_cbranch_vccnz .LBB0_560
	s_nop 3
	ds_read_b128 v[88:91], v133
	ds_read_b128 v[92:95], v142
	ds_read_b128 v[96:99], v133 offset:64
	ds_read_b128 v[100:103], v142 offset:64
	ds_read_b128 v[104:107], v133 offset:128
	ds_read_b128 v[180:183], v142 offset:128
	ds_read_b128 v[78:81], v133 offset:192
	ds_read_b128 v[184:187], v142 offset:192
	s_and_b64 vcc, s[40:41], s[50:51]
	s_waitcnt lgkmcnt(6)
	v_mfma_f32_16x16x32_bf16 v[74:77], v[88:91], v[92:95], 0
	s_waitcnt lgkmcnt(4)
	v_mfma_f32_16x16x32_bf16 v[74:77], v[96:99], v[100:103], v[74:77]
	s_waitcnt lgkmcnt(2)
	v_mfma_f32_16x16x32_bf16 v[74:77], v[104:107], v[180:183], v[74:77]
	s_waitcnt lgkmcnt(0)
	v_mfma_f32_16x16x32_bf16 v[74:77], v[78:81], v[184:187], v[74:77]
	v_mov_b32_e32 v78, s35
	s_nop 6
	v_cndmask_b32_e64 v63, v75, 0, s[52:53]
	v_cndmask_b32_e64 v67, v76, 0, s[54:55]
	v_cndmask_b32_e64 v79, v77, 0, s[56:57]
	v_cndmask_b32_e64 v77, v77, v79, s[40:41]
	v_cndmask_b32_e64 v67, v76, v67, s[40:41]
	v_cndmask_b32_e32 v74, v74, v78, vcc
	v_cndmask_b32_e64 v63, v75, v63, s[40:41]
	v_cvt_pk_bf16_f32 v74, v74, v63
	v_cvt_pk_bf16_f32 v75, v67, v77
	s_waitcnt lgkmcnt(0)
.LBB0_560:
	s_andn2_b64 vcc, exec, s[30:31]
	v_mov_b32_e32 v67, 0
	ds_write_b64 v143, v[74:75]
	s_cbranch_vccnz .LBB0_562
	s_nop 3
	ds_read_b128 v[88:91], v134
	ds_read_b128 v[92:95], v142
	ds_read_b128 v[96:99], v134 offset:64
	ds_read_b128 v[100:103], v142 offset:64
	ds_read_b128 v[104:107], v134 offset:128
	ds_read_b128 v[180:183], v142 offset:128
	ds_read_b128 v[78:81], v134 offset:192
	ds_read_b128 v[184:187], v142 offset:192
	v_mov_b32_e32 v66, s35
	s_and_b64 vcc, s[48:49], s[50:51]
	s_waitcnt lgkmcnt(6)
	v_mfma_f32_16x16x32_bf16 v[74:77], v[88:91], v[92:95], 0
	s_waitcnt lgkmcnt(4)
	v_mfma_f32_16x16x32_bf16 v[74:77], v[96:99], v[100:103], v[74:77]
	s_waitcnt lgkmcnt(2)
	v_mfma_f32_16x16x32_bf16 v[74:77], v[104:107], v[180:183], v[74:77]
	s_waitcnt lgkmcnt(0)
	v_mfma_f32_16x16x32_bf16 v[74:77], v[78:81], v[184:187], v[74:77]
	s_nop 7
	v_cndmask_b32_e64 v63, v75, 0, s[52:53]
	v_cndmask_b32_e64 v67, v76, 0, s[54:55]
	v_cndmask_b32_e64 v78, v77, 0, s[56:57]
	v_cndmask_b32_e64 v77, v77, v78, s[48:49]
	v_cndmask_b32_e64 v67, v76, v67, s[48:49]
	v_cndmask_b32_e32 v66, v74, v66, vcc
	v_cndmask_b32_e64 v63, v75, v63, s[48:49]
	v_cvt_pk_bf16_f32 v66, v66, v63
	v_cvt_pk_bf16_f32 v67, v67, v77
	s_waitcnt lgkmcnt(0)
.LBB0_562:
	ds_write_b64 v144, v[66:67]
	s_waitcnt lgkmcnt(0)
	s_barrier
	s_nop 2
	ds_read_b128 v[84:87], v173
	ds_read_b128 v[88:91], v145 offset:52224
	ds_read_b128 v[92:95], v146 offset:52224
	ds_read_b128 v[96:99], v147 offset:52224
	ds_read_b128 v[100:103], v148 offset:52224
	ds_read_b128 v[104:107], v149
	ds_read_b128 v[180:183], v150 offset:52224
	ds_read_b128 v[184:187], v151 offset:52224
	ds_read_b128 v[200:203], v152 offset:52224
	ds_read_b128 v[204:207], v153 offset:52224
	ds_read_b128 v[208:211], v135
	ds_read_b128 v[212:215], v154
	v_and_b32_e32 v66, 64, v195
	v_xor_b32_e32 v63, 16, v195
	s_waitcnt lgkmcnt(10)
	v_mfma_f32_16x16x32_bf16 v[38:41], v[88:91], v[84:87], v[38:41]
	ds_read_b128 v[88:91], v154 offset:4352
	v_add_u32_e32 v66, 64, v66
	v_cmp_lt_i32_e32 vcc, v63, v66
	s_waitcnt lgkmcnt(10)
	v_mfma_f32_16x16x32_bf16 v[34:37], v[92:95], v[84:87], v[34:37]
	ds_read_b128 v[92:95], v154 offset:8704
	v_cndmask_b32_e32 v63, v195, v63, vcc
	v_lshlrev_b32_e32 v63, 2, v63
	s_waitcnt lgkmcnt(10)
	v_mfma_f32_16x16x32_bf16 v[30:33], v[96:99], v[84:87], v[30:33]
	ds_read_b128 v[96:99], v154 offset:13056
	s_waitcnt lgkmcnt(10)
	v_mfma_f32_16x16x32_bf16 v[26:29], v[100:103], v[84:87], v[26:29]
	ds_read_b128 v[84:87], v135 offset:64
	ds_read_b128 v[100:103], v172
	s_waitcnt lgkmcnt(10)
	v_mfma_f32_16x16x32_bf16 v[38:41], v[180:183], v[104:107], v[38:41]
	ds_read_b128 v[180:183], v171
	s_waitcnt lgkmcnt(10)
	v_mfma_f32_16x16x32_bf16 v[34:37], v[184:187], v[104:107], v[34:37]
	ds_read_b128 v[184:187], v170
	s_waitcnt lgkmcnt(10)
	v_mfma_f32_16x16x32_bf16 v[30:33], v[200:203], v[104:107], v[30:33]
	ds_read_b128 v[200:203], v169
	s_waitcnt lgkmcnt(10)
	v_mfma_f32_16x16x32_bf16 v[26:29], v[204:207], v[104:107], v[26:29]
	ds_read_b128 v[104:107], v135 offset:128
	ds_read_b128 v[204:207], v168
	s_waitcnt lgkmcnt(10)
	v_mfma_f32_16x16x32_bf16 v[38:41], v[212:215], v[208:211], v[38:41]
	ds_read_b128 v[212:215], v158
	s_waitcnt lgkmcnt(10)
	v_mfma_f32_16x16x32_bf16 v[34:37], v[88:91], v[208:211], v[34:37]
	ds_read_b128 v[88:91], v166
	s_waitcnt lgkmcnt(10)
	v_mfma_f32_16x16x32_bf16 v[30:33], v[92:95], v[208:211], v[30:33]
	ds_read_b128 v[92:95], v167
	s_waitcnt lgkmcnt(10)
	v_mfma_f32_16x16x32_bf16 v[26:29], v[96:99], v[208:211], v[26:29]
	ds_read_b128 v[96:99], v135 offset:192
	ds_read_b128 v[208:211], v157
	s_waitcnt lgkmcnt(10)
	v_mfma_f32_16x16x32_bf16 v[38:41], v[100:103], v[84:87], v[38:41]
	ds_read_b128 v[100:103], v155
	s_waitcnt lgkmcnt(10)
	v_mfma_f32_16x16x32_bf16 v[34:37], v[180:183], v[84:87], v[34:37]
	ds_read_b128 v[180:183], v156
	s_waitcnt lgkmcnt(10)
	v_mfma_f32_16x16x32_bf16 v[30:33], v[184:187], v[84:87], v[30:33]
	ds_read_b128 v[184:187], v61
	s_waitcnt lgkmcnt(10)
	v_mfma_f32_16x16x32_bf16 v[26:29], v[200:203], v[84:87], v[26:29]
	s_waitcnt lgkmcnt(8)
	v_mfma_f32_16x16x32_bf16 v[38:41], v[204:207], v[104:107], v[38:41]
	s_waitcnt lgkmcnt(7)
	v_mfma_f32_16x16x32_bf16 v[34:37], v[212:215], v[104:107], v[34:37]
	s_waitcnt lgkmcnt(6)
	v_mfma_f32_16x16x32_bf16 v[30:33], v[88:91], v[104:107], v[30:33]
	s_waitcnt lgkmcnt(5)
	v_mfma_f32_16x16x32_bf16 v[26:29], v[92:95], v[104:107], v[26:29]
	s_waitcnt lgkmcnt(3)
	v_mfma_f32_16x16x32_bf16 v[38:41], v[208:211], v[96:99], v[38:41]
	s_waitcnt lgkmcnt(2)
	v_mfma_f32_16x16x32_bf16 v[34:37], v[100:103], v[96:99], v[34:37]
	s_waitcnt lgkmcnt(1)
	v_mfma_f32_16x16x32_bf16 v[30:33], v[180:183], v[96:99], v[30:33]
	s_nop 3
	v_mul_f32_e32 v61, v39, v39
	v_fmac_f32_e32 v61, v38, v38
	v_fmac_f32_e32 v61, v40, v40
	v_fmac_f32_e32 v61, v41, v41
	v_fmac_f32_e32 v61, v34, v34
	v_fmac_f32_e32 v61, v35, v35
	v_fmac_f32_e32 v61, v36, v36
	v_fmac_f32_e32 v61, v37, v37
	s_waitcnt lgkmcnt(0)
	v_mfma_f32_16x16x32_bf16 v[26:29], v[184:187], v[96:99], v[26:29]
	v_fmac_f32_e32 v61, v30, v30
	v_fmac_f32_e32 v61, v31, v31
	v_fmac_f32_e32 v61, v32, v32
	v_fmac_f32_e32 v61, v33, v33
	s_nop 3
	v_fmac_f32_e32 v61, v26, v26
	v_fmac_f32_e32 v61, v27, v27
	v_fmac_f32_e32 v61, v28, v28
	v_fmac_f32_e32 v61, v29, v29
	s_waitcnt lgkmcnt(0)
	ds_bpermute_b32 v63, v63, v61
	s_barrier
	s_waitcnt lgkmcnt(0)
	v_add_f32_e32 v61, v61, v63
	v_xor_b32_e32 v63, 32, v195
	v_cmp_lt_i32_e32 vcc, v63, v66
	s_nop 1
	v_cndmask_b32_e32 v63, v195, v63, vcc
	v_lshlrev_b32_e32 v63, 2, v63
	ds_bpermute_b32 v63, v63, v61
	s_and_saveexec_b64 s[0:1], s[58:59]
	s_cbranch_execz .LBB0_477
	s_waitcnt lgkmcnt(0)
	v_add_f32_e32 v61, v61, v63
	ds_write_b32 v136, v61
	s_branch .LBB0_477

; #define LAS __attribute__((address_space(3)))
; #define BAR_LDS() do { asm volatile("s_waitcnt lgkmcnt(0)" ::: "memory"); __builtin_amdgcn_s_barrier(); asm volatile("" ::: "memory"); } while (0)
; __device__ __forceinline__ float bf2f(unsigned h) { return __uint_as_float(h << 16); }
; __device__ __forceinline__ unsigned pk2(float lo, float hi) { return pg8::cvt_pk_bf16(lo, hi); }
; __device__ __forceinline__ void ret_out_item(const Ctx& X, const bf16* H, bf16* Y, int l, int it, RetOutRegs& R, bool has_next) {
;     ...
;         const float rstd = __builtin_amdgcn_rsqf((red[(ps * 8 + X.wave) * 16 + fr] + red[(ps * 8 + (X.wave ^ 4)) * 16 + fr]) * (1.0f / 128.0f) + EPS);
; #pragma unroll
;         for (int t = 0; t < 4; ++t) { const int v = 64 * vh + 16 * t + 4 * fq; const f32x4 g4 = *(const f32x4*)(gn + v);
;             const float g0 = bf2f(gw[ps][t].x & 0xffffu), g1 = bf2f(gw[ps][t].x >> 16), g2 = bf2f(gw[ps][t].y & 0xffffu), g3 = bf2f(gw[ps][t].y >> 16);
;             const float y0 = (o[t][0] - mu) * rstd * g4.x * (g0 * __builtin_amdgcn_rcpf(1.0f + __expf(-g0))), y1 = (o[t][1] - mu) * rstd * g4.y * (g1 * __builtin_amdgcn_rcpf(1.0f + __expf(-g1)));
;             const float y2 = (o[t][2] - mu) * rstd * g4.z * (g2 * __builtin_amdgcn_rcpf(1.0f + __expf(-g2))), y3 = (o[t][3] - mu) * rstd * g4.w * (g3 * __builtin_amdgcn_rcpf(1.0f + __expf(-g3)));
;             v2u w; w.x = pk2(y0, y1); w.y = pk2(y2, y3); *(LAS v2u*)(AM + tok * 272 + v * 2) = w; } }
;     BAR_LDS();
; #pragma unroll
;     for (int p = 0; p < 4; ++p) { const int idx = X.tid + NTHR * p, row = idx >> 4, c8 = idx & 15; *(v4u*)(Y + (m0 + row) * D + ycol + 8 * c8) = *(const LAS v4u*)(AM + row * 272 + c8 * 16); }
.LBB0_568:
	s_or_b64 exec, exec, s[0:1]
	s_waitcnt lgkmcnt(0)
	s_barrier
	ds_read_b32 v40, v153 offset:512
	s_waitcnt lgkmcnt(1)
	ds_read_b32 v41, v172 offset:512
	global_load_dwordx4 v[52:55], v[140:141], off
	global_load_dwordx4 v[232:235], v[140:141], off offset:64
	global_load_dwordx4 v[236:239], v[140:141], off offset:128
	global_load_dwordx4 v[240:243], v[140:141], off offset:192
	v_lshlrev_b32_e32 v56, 16, v138
	v_and_b32_e32 v57, 0xffff0000, v138
	s_lshl_b64 s[0:1], s[22:23], 1
	s_waitcnt lgkmcnt(0)
	v_add_f32_e32 v40, v40, v41
	v_mul_f32_e32 v41, 0xbfb8aa3b, v56
	v_fmamk_f32 v40, v40, 0x3c000000, v1
	v_exp_f32_e32 v41, v41
	v_rsq_f32_e32 v40, v40
	s_add_u32 s0, s28, s0
	s_addc_u32 s1, s29, s1
	v_add_f32_e32 v41, 1.0, v41
	v_rcp_f32_e32 v58, v41
	v_pk_mul_f32 v[50:51], v[50:51], v[40:41] op_sel_hi:[1,0]
	v_mul_f32_e32 v41, 0xbfb8aa3b, v57
	v_exp_f32_e32 v41, v41
	s_andn2_b64 vcc, exec, s[18:19]
	v_add_f32_e32 v41, 1.0, v41
	v_rcp_f32_e32 v59, v41
	s_waitcnt vmcnt(3)
	v_pk_mul_f32 v[50:51], v[52:53], v[50:51]
	v_pk_mul_f32 v[52:53], v[58:59], v[56:57]
	s_nop 0
	v_pk_mul_f32 v[50:51], v[52:53], v[50:51]
	v_lshlrev_b32_e32 v52, 16, v139
	v_mul_f32_e32 v41, 0xbfb8aa3b, v52
	v_exp_f32_e32 v41, v41
	v_and_b32_e32 v53, 0xffff0000, v139
	v_cvt_pk_bf16_f32 v50, v50, v51
	v_add_f32_e32 v41, 1.0, v41
	v_rcp_f32_e32 v56, v41
	v_pk_mul_f32 v[48:49], v[48:49], v[40:41] op_sel_hi:[1,0]
	v_mul_f32_e32 v41, 0xbfb8aa3b, v53
	v_exp_f32_e32 v41, v41
	v_pk_mul_f32 v[48:49], v[54:55], v[48:49]
	v_add_f32_e32 v41, 1.0, v41
	v_rcp_f32_e32 v57, v41
	v_add_u32_e32 v41, v189, v185
	v_pk_mul_f32 v[52:53], v[56:57], v[52:53]
	s_nop 0
	v_pk_mul_f32 v[48:49], v[52:53], v[48:49]
	v_lshlrev_b32_e32 v52, 16, v136
	v_cvt_pk_bf16_f32 v51, v48, v49
	ds_write_b64 v41, v[50:51]
	v_mul_f32_e32 v41, 0xbfb8aa3b, v52
	v_exp_f32_e32 v41, v41
	v_and_b32_e32 v53, 0xffff0000, v136
	v_add_f32_e32 v41, 1.0, v41
	v_rcp_f32_e32 v54, v41
	v_pk_mul_f32 v[46:47], v[46:47], v[40:41] op_sel_hi:[1,0]
	v_mul_f32_e32 v41, 0xbfb8aa3b, v53
	v_exp_f32_e32 v41, v41
	s_waitcnt vmcnt(2)
	v_pk_mul_f32 v[46:47], v[232:233], v[46:47]
	v_add_f32_e32 v41, 1.0, v41
	v_rcp_f32_e32 v55, v41
	s_nop 0
	v_pk_mul_f32 v[48:49], v[54:55], v[52:53]
	s_nop 0
	v_pk_mul_f32 v[46:47], v[48:49], v[46:47]
	v_lshlrev_b32_e32 v48, 16, v137
	v_mul_f32_e32 v41, 0xbfb8aa3b, v48
	v_exp_f32_e32 v41, v41
	v_and_b32_e32 v49, 0xffff0000, v137
	v_cvt_pk_bf16_f32 v46, v46, v47
	v_add_f32_e32 v41, 1.0, v41
	v_rcp_f32_e32 v52, v41
	v_pk_mul_f32 v[44:45], v[44:45], v[40:41] op_sel_hi:[1,0]
	v_mul_f32_e32 v41, 0xbfb8aa3b, v49
	v_exp_f32_e32 v41, v41
	v_pk_mul_f32 v[44:45], v[234:235], v[44:45]
	v_add_f32_e32 v41, 1.0, v41
	v_rcp_f32_e32 v53, v41
	v_add_u32_e32 v41, v189, v186
	v_pk_mul_f32 v[48:49], v[52:53], v[48:49]
	s_nop 0
	v_pk_mul_f32 v[44:45], v[48:49], v[44:45]
	v_lshlrev_b32_e32 v48, 16, v134
	v_cvt_pk_bf16_f32 v47, v44, v45
	ds_write_b64 v41, v[46:47]
	v_mul_f32_e32 v41, 0xbfb8aa3b, v48
	v_exp_f32_e32 v41, v41
	v_and_b32_e32 v49, 0xffff0000, v134
	v_add_f32_e32 v41, 1.0, v41
	v_rcp_f32_e32 v50, v41
	v_pk_mul_f32 v[36:37], v[36:37], v[40:41] op_sel_hi:[1,0]
	v_mul_f32_e32 v41, 0xbfb8aa3b, v49
	v_exp_f32_e32 v41, v41
	s_waitcnt vmcnt(1)
	v_pk_mul_f32 v[36:37], v[36:37], v[236:237]
	v_add_f32_e32 v41, 1.0, v41
	v_rcp_f32_e32 v51, v41
	s_nop 0
	v_pk_mul_f32 v[44:45], v[50:51], v[48:49]
	s_nop 0
	v_pk_mul_f32 v[36:37], v[44:45], v[36:37]
	v_lshlrev_b32_e32 v44, 16, v135
	v_mul_f32_e32 v41, 0xbfb8aa3b, v44
	v_exp_f32_e32 v41, v41
	v_and_b32_e32 v45, 0xffff0000, v135
	v_cvt_pk_bf16_f32 v36, v36, v37
	v_add_f32_e32 v41, 1.0, v41
	v_rcp_f32_e32 v48, v41
	v_pk_mul_f32 v[34:35], v[34:35], v[40:41] op_sel_hi:[1,0]
	v_mul_f32_e32 v41, 0xbfb8aa3b, v45
	v_exp_f32_e32 v41, v41
	v_pk_mul_f32 v[34:35], v[34:35], v[238:239]
	v_add_f32_e32 v41, 1.0, v41
	v_rcp_f32_e32 v49, v41
	s_nop 0
	v_pk_mul_f32 v[44:45], v[48:49], v[44:45]
	s_nop 0
	v_pk_mul_f32 v[34:35], v[44:45], v[34:35]
	v_lshlrev_b32_e32 v44, 16, v132
	v_cvt_pk_bf16_f32 v37, v34, v35
	v_add_u32_e32 v34, v189, v187
	ds_write_b64 v34, v[36:37]
	v_mul_f32_e32 v41, 0xbfb8aa3b, v44
	v_exp_f32_e32 v41, v41
	v_and_b32_e32 v45, 0xffff0000, v132
	v_add_f32_e32 v41, 1.0, v41
	v_rcp_f32_e32 v46, v41
	v_pk_mul_f32 v[42:43], v[42:43], v[40:41] op_sel_hi:[1,0]
	v_mul_f32_e32 v41, 0xbfb8aa3b, v45
	v_exp_f32_e32 v41, v41
	s_waitcnt vmcnt(0)
	v_pk_mul_f32 v[34:35], v[42:43], v[240:241]
	v_add_f32_e32 v41, 1.0, v41
	v_rcp_f32_e32 v47, v41
	s_nop 0
	v_pk_mul_f32 v[42:43], v[46:47], v[44:45]
	s_nop 0
	v_pk_mul_f32 v[34:35], v[42:43], v[34:35]
	v_lshlrev_b32_e32 v42, 16, v133
	v_mul_f32_e32 v41, 0xbfb8aa3b, v42
	v_exp_f32_e32 v41, v41
	v_and_b32_e32 v43, 0xffff0000, v133
	v_cvt_pk_bf16_f32 v34, v34, v35
	v_add_f32_e32 v41, 1.0, v41
	v_pk_mul_f32 v[38:39], v[38:39], v[40:41] op_sel_hi:[1,0]
	v_rcp_f32_e32 v44, v41
	v_pk_mul_f32 v[36:37], v[38:39], v[242:243]
	v_mul_f32_e32 v38, 0xbfb8aa3b, v43
	v_exp_f32_e32 v38, v38
	s_nop 0
	v_add_f32_e32 v38, 1.0, v38
	v_rcp_f32_e32 v45, v38
	s_nop 0
	v_pk_mul_f32 v[38:39], v[44:45], v[42:43]
	s_nop 0
	v_pk_mul_f32 v[36:37], v[38:39], v[36:37]
	v_lshl_add_u64 v[38:39], s[12:13], 0, v[106:107]
	v_cvt_pk_bf16_f32 v35, v36, v37
	v_add_u32_e32 v36, v189, v188
	ds_write_b64 v36, v[34:35]
	s_waitcnt lgkmcnt(0)
	s_barrier
	ds_read_b128 v[40:43], v210
	ds_read_b128 v[44:47], v211
	ds_read_b128 v[56:59], v212
	ds_read_b128 v[60:63], v213
	v_lshlrev_b64 v[38:39], 12, v[38:39]
	v_lshl_add_u64 v[38:39], s[0:1], 0, v[38:39]
	v_lshl_add_u64 v[38:39], v[38:39], 0, v[158:159]
	s_waitcnt lgkmcnt(3)
	global_store_dwordx4 v[38:39], v[40:43], off offset:1536
	v_lshl_add_u64 v[38:39], s[12:13], 0, v[108:109]
	v_lshlrev_b64 v[38:39], 12, v[38:39]
	v_lshl_add_u64 v[38:39], s[0:1], 0, v[38:39]
	v_lshl_add_u64 v[38:39], v[38:39], 0, v[158:159]
	s_waitcnt lgkmcnt(2)
	global_store_dwordx4 v[38:39], v[44:47], off offset:1536
	v_lshl_add_u64 v[38:39], s[12:13], 0, v[110:111]
	v_lshlrev_b64 v[38:39], 12, v[38:39]
	v_lshl_add_u64 v[38:39], s[0:1], 0, v[38:39]
	v_lshl_add_u64 v[38:39], v[38:39], 0, v[158:159]
	s_waitcnt lgkmcnt(1)
	global_store_dwordx4 v[38:39], v[56:59], off offset:1536
	v_lshl_add_u64 v[38:39], s[12:13], 0, v[112:113]
	v_lshlrev_b64 v[38:39], 12, v[38:39]
	v_lshl_add_u64 v[38:39], s[0:1], 0, v[38:39]
	v_lshl_add_u64 v[38:39], v[38:39], 0, v[158:159]
	s_waitcnt lgkmcnt(0)
	global_store_dwordx4 v[38:39], v[60:63], off offset:1536
	s_waitcnt lgkmcnt(0)
	s_barrier
	s_mov_b32 s0, s38
	s_cbranch_vccz .LBB0_597
